# diff-attn FAST epilogue rewritten: rows split between partner waves, all zb/gsub loads issued up front, DPP+permlane16 reductions instead of serial ds_bpermute, saddr-form loads/stores
# speedup vs baseline: 1.0792x; 1.0319x over previous
.Lda_loop:
	s_waitcnt lgkmcnt(5)
	v_mfma_f32_32x32x16_bf16 v[96:111], v[194:197], v[124:127], 0
	v_exp_f32_e32 v72, v72
	v_exp_f32_e32 v73, v73
	ds_read_b128 v[218:221], v143 offset:24576
	s_waitcnt lgkmcnt(5)
	v_mfma_f32_32x32x16_bf16 v[96:111], v[198:201], v[120:123], v[96:111]
	v_exp_f32_e32 v74, v74
	v_exp_f32_e32 v75, v75
	v_add_f32_e32 v234, v234, v72
	ds_read_b128 v[222:225], v141 offset:24576
	ds_read_b64_tr_b16 v[226:227], v151 offset:0
	ds_read_b64_tr_b16 v[228:229], v151 offset:2048
	s_waitcnt lgkmcnt(7)
	v_mfma_f32_32x32x16_bf16 v[96:111], v[202:205], v[116:119], v[96:111]
	v_exp_f32_e32 v76, v76
	v_exp_f32_e32 v77, v77
	v_add_f32_e32 v235, v235, v73
	v_add_f32_e32 v234, v234, v74
	ds_read_b64_tr_b16 v[230:231], v151 offset:512
	ds_read_b64_tr_b16 v[232:233], v151 offset:2560
	s_waitcnt lgkmcnt(8)
	v_mfma_f32_32x32x16_bf16 v[96:111], v[206:209], v[112:115], v[96:111]
	v_exp_f32_e32 v78, v78
	v_exp_f32_e32 v79, v79
	v_add_f32_e32 v235, v235, v75
	v_add_f32_e32 v234, v234, v76
	ds_read_b64_tr_b16 v[238:239], v151 offset:1024
	ds_read_b64_tr_b16 v[240:241], v151 offset:3072
	s_waitcnt lgkmcnt(9)
	v_mfma_f32_32x32x16_bf16 v[162:177], v[210:213], v[124:127], 0
	v_add_f32_e32 v235, v235, v77
	v_add_f32_e32 v234, v234, v78
	v_add_f32_e32 v235, v235, v79
	v_cvt_pk_bf16_f32 v182, v72, v73
	v_cvt_pk_bf16_f32 v184, v76, v77
	ds_read_b64_tr_b16 v[242:243], v151 offset:1536
	ds_read_b64_tr_b16 v[244:245], v151 offset:3584
	s_waitcnt lgkmcnt(10)
	v_mfma_f32_32x32x16_bf16 v[162:177], v[214:217], v[120:123], v[162:177]
	v_cvt_pk_bf16_f32 v183, v74, v75
	v_cvt_pk_bf16_f32 v185, v78, v79
	v_permlane32_swap_b32_e32 v182, v184
	ds_read_b64_tr_b16 v[246:247], v151 offset:4096
	ds_read_b64_tr_b16 v[248:249], v151 offset:6144
	v_permlane32_swap_b32_e32 v183, v185
	s_waitcnt lgkmcnt(11)
	v_mfma_f32_32x32x16_bf16 v[162:177], v[218:221], v[116:119], v[162:177]
	v_exp_f32_e32 v80, v80
	v_exp_f32_e32 v81, v81
	ds_read_b64_tr_b16 v[250:251], v151 offset:4608
	ds_read_b64_tr_b16 v[252:253], v151 offset:6656
	s_waitcnt lgkmcnt(12)
	v_mfma_f32_32x32x16_bf16 v[162:177], v[222:225], v[112:115], v[162:177]
	v_exp_f32_e32 v82, v82
	v_exp_f32_e32 v83, v83
	v_add_f32_e32 v234, v234, v80
	ds_read_b64_tr_b16 v[152:153], v151 offset:5120
	ds_read_b64_tr_b16 v[154:155], v151 offset:7168
	s_waitcnt lgkmcnt(12)
	v_mfma_f32_32x32x16_bf16 v[48:63], v[178:181], v[226:229], v[48:63]
	v_exp_f32_e32 v84, v84
	v_exp_f32_e32 v85, v85
	v_add_f32_e32 v235, v235, v81
	v_add_f32_e32 v234, v234, v82
	ds_read_b64_tr_b16 v[226:227], v151 offset:5632
	ds_read_b64_tr_b16 v[228:229], v151 offset:7680
	s_waitcnt lgkmcnt(12)
	v_mfma_f32_32x32x16_bf16 v[32:47], v[178:181], v[230:233], v[32:47]
	v_exp_f32_e32 v86, v86
	v_exp_f32_e32 v87, v87
	v_add_f32_e32 v235, v235, v83
	v_add_f32_e32 v234, v234, v84
	ds_read_b64_tr_b16 v[230:231], v151 offset:8192
	ds_read_b64_tr_b16 v[232:233], v151 offset:10240
	s_waitcnt lgkmcnt(12)
	v_mfma_f32_32x32x16_bf16 v[16:31], v[178:181], v[238:241], v[16:31]
	v_add_f32_e32 v235, v235, v85
	v_add_f32_e32 v234, v234, v86
	v_add_f32_e32 v235, v235, v87
	v_cvt_pk_bf16_f32 v186, v80, v81
	v_cvt_pk_bf16_f32 v188, v84, v85
	ds_read_b64_tr_b16 v[238:239], v151 offset:8704
	ds_read_b64_tr_b16 v[240:241], v151 offset:10752
	s_waitcnt lgkmcnt(12)
	v_mfma_f32_32x32x16_bf16 v[0:15], v[178:181], v[242:245], v[0:15]
	v_cvt_pk_bf16_f32 v187, v82, v83
	v_cvt_pk_bf16_f32 v189, v86, v87
	v_permlane32_swap_b32_e32 v186, v188
	ds_read_b64_tr_b16 v[242:243], v151 offset:9216
	ds_read_b64_tr_b16 v[244:245], v151 offset:11264
	v_permlane32_swap_b32_e32 v187, v189
	s_waitcnt lgkmcnt(12)
	v_mfma_f32_32x32x16_bf16 v[48:63], v[182:185], v[246:249], v[48:63]
	v_exp_f32_e32 v88, v88
	v_exp_f32_e32 v89, v89
	ds_read_b64_tr_b16 v[246:247], v151 offset:9728
	ds_read_b64_tr_b16 v[248:249], v151 offset:11776
	s_waitcnt lgkmcnt(12)
	v_mfma_f32_32x32x16_bf16 v[32:47], v[182:185], v[250:253], v[32:47]
	v_exp_f32_e32 v90, v90
	v_exp_f32_e32 v91, v91
	v_add_f32_e32 v234, v234, v88
	ds_read_b64_tr_b16 v[250:251], v151 offset:12288
	ds_read_b64_tr_b16 v[252:253], v151 offset:14336
	s_waitcnt lgkmcnt(12)
	v_mfma_f32_32x32x16_bf16 v[16:31], v[182:185], v[152:155], v[16:31]
	v_exp_f32_e32 v92, v92
	v_exp_f32_e32 v93, v93
	v_add_f32_e32 v235, v235, v89
	v_add_f32_e32 v234, v234, v90
	ds_read_b64_tr_b16 v[152:153], v151 offset:12800
	ds_read_b64_tr_b16 v[154:155], v151 offset:14848
	s_waitcnt lgkmcnt(12)
	v_mfma_f32_32x32x16_bf16 v[0:15], v[182:185], v[226:229], v[0:15]
	v_exp_f32_e32 v94, v94
	v_exp_f32_e32 v95, v95
	v_add_f32_e32 v235, v235, v91
	v_add_f32_e32 v234, v234, v92
	ds_read_b64_tr_b16 v[226:227], v151 offset:13312
	ds_read_b64_tr_b16 v[228:229], v151 offset:15360
	s_waitcnt lgkmcnt(12)
	v_mfma_f32_32x32x16_bf16 v[48:63], v[186:189], v[230:233], v[48:63]
	v_add_f32_e32 v235, v235, v93
	v_add_f32_e32 v234, v234, v94
	v_add_f32_e32 v235, v235, v95
	v_cvt_pk_bf16_f32 v190, v88, v89
	v_cvt_pk_bf16_f32 v192, v92, v93
	ds_read_b64_tr_b16 v[230:231], v151 offset:13824
	ds_read_b64_tr_b16 v[232:233], v151 offset:15872
	s_waitcnt lgkmcnt(12)
	v_mfma_f32_32x32x16_bf16 v[32:47], v[186:189], v[238:241], v[32:47]
	s_waitcnt vmcnt(0)
	s_barrier
	s_add_i32 s63, s62, 0xc000
	s_cmp_ge_u32 s63, 0x14000
	s_cselect_b32 s69, 0x14000, 0
	s_sub_i32 s63, s63, s69
	s_add_i32 s68, s62, 0x10000
	s_cmp_ge_u32 s68, 0x14000
	s_cselect_b32 s69, 0x14000, 0
	s_sub_i32 s68, s68, s69
	s_add_i32 s62, s62, 0x4000
	s_cmp_ge_u32 s62, 0x14000
	s_cselect_b32 s69, 0x14000, 0
	s_sub_i32 s62, s62, s69
	v_add_u32_e32 v151, s62, v140
	v_cvt_pk_bf16_f32 v191, v90, v91
	v_cvt_pk_bf16_f32 v193, v94, v95
	v_permlane32_swap_b32_e32 v190, v192
	s_nop 0
	v_permlane32_swap_b32_e32 v191, v193
	s_add_i32 m0, s41, s63
	v_lshl_add_u64 v[146:147], v[132:133], 0, s[42:43]
	global_load_lds_dwordx4 v[146:147], off
	s_waitcnt lgkmcnt(10)
	v_mfma_f32_32x32x16_bf16 v[16:31], v[186:189], v[242:245], v[16:31]
	v_exp_f32_e32 v96, v96
	v_exp_f32_e32 v97, v97
	ds_read_b128 v[194:197], v149 offset:32768
	s_add_i32 m0, s71, s63
	v_lshl_add_u64 v[254:255], v[132:133], 0, s[46:47]
	global_load_lds_dwordx4 v[254:255], off
	s_waitcnt lgkmcnt(9)
	v_mfma_f32_32x32x16_bf16 v[0:15], v[186:189], v[246:249], v[0:15]
	v_exp_f32_e32 v98, v98
	v_exp_f32_e32 v99, v99
	v_add_f32_e32 v234, v234, v96
	ds_read_b128 v[198:201], v148 offset:32768
	s_add_i32 m0, s40, 0x0
	v_lshl_add_u64 v[146:147], v[134:135], 0, s[84:85]
	global_load_lds_dwordx4 v[146:147], off
	s_waitcnt lgkmcnt(8)
	v_mfma_f32_32x32x16_bf16 v[48:63], v[190:193], v[250:253], v[48:63]
	v_exp_f32_e32 v100, v100
	v_exp_f32_e32 v101, v101
	v_add_f32_e32 v235, v235, v97
	v_add_f32_e32 v234, v234, v98
	ds_read_b128 v[202:205], v143 offset:32768
	s_add_i32 m0, s40, 0x2000
	v_lshl_add_u64 v[254:255], v[134:135], 0, s[86:87]
	global_load_lds_dwordx4 v[254:255], off
	s_waitcnt lgkmcnt(7)
	v_mfma_f32_32x32x16_bf16 v[32:47], v[190:193], v[152:155], v[32:47]
	v_exp_f32_e32 v102, v102
	v_exp_f32_e32 v103, v103
	v_add_f32_e32 v235, v235, v99
	v_add_f32_e32 v234, v234, v100
	ds_read_b128 v[206:209], v141 offset:32768
	s_add_i32 m0, s41, s68
	v_lshl_add_u64 v[146:147], v[132:133], 0, s[88:89]
	global_load_lds_dwordx4 v[146:147], off
	s_waitcnt lgkmcnt(6)
	v_mfma_f32_32x32x16_bf16 v[16:31], v[190:193], v[226:229], v[16:31]
	v_add_f32_e32 v235, v235, v101
	v_add_f32_e32 v234, v234, v102
	v_add_f32_e32 v235, v235, v103
	v_cvt_pk_bf16_f32 v178, v96, v97
	v_cvt_pk_bf16_f32 v180, v100, v101
	ds_read_b128 v[210:213], v149 offset:40960
	s_add_i32 m0, s71, s68
	v_lshl_add_u64 v[254:255], v[132:133], 0, s[90:91]
	global_load_lds_dwordx4 v[254:255], off
	s_waitcnt lgkmcnt(5)
	v_mfma_f32_32x32x16_bf16 v[0:15], v[190:193], v[230:233], v[0:15]
	v_cvt_pk_bf16_f32 v179, v98, v99
	v_cvt_pk_bf16_f32 v181, v102, v103
	v_permlane32_swap_b32_e32 v178, v180
	ds_read_b128 v[214:217], v148 offset:40960
	v_permlane32_swap_b32_e32 v179, v181
	s_add_i32 m0, s40, 0x4000
	v_lshl_add_u64 v[146:147], v[134:135], 0, s[92:93]
	global_load_lds_dwordx4 v[146:147], off
	s_add_i32 m0, s40, 0x6000
	v_lshl_add_u64 v[254:255], v[134:135], 0, s[94:95]
	global_load_lds_dwordx4 v[254:255], off
	v_lshl_add_u64 v[132:133], v[132:133], 0, s[12:13]
	v_lshl_add_u64 v[134:135], v[134:135], 0, s[12:13]
	s_waitcnt lgkmcnt(5)
	v_mfma_f32_32x32x16_bf16 v[64:79], v[194:197], v[124:127], 0
	v_exp_f32_e32 v104, v104
	v_exp_f32_e32 v105, v105
	ds_read_b128 v[218:221], v143 offset:40960
	s_waitcnt lgkmcnt(5)
	v_mfma_f32_32x32x16_bf16 v[64:79], v[198:201], v[120:123], v[64:79]
	v_exp_f32_e32 v106, v106
	v_exp_f32_e32 v107, v107
	v_add_f32_e32 v234, v234, v104
	ds_read_b128 v[222:225], v141 offset:40960
	ds_read_b64_tr_b16 v[226:227], v151 offset:0
	ds_read_b64_tr_b16 v[228:229], v151 offset:2048
	s_waitcnt lgkmcnt(7)
	v_mfma_f32_32x32x16_bf16 v[64:79], v[202:205], v[116:119], v[64:79]
	v_exp_f32_e32 v108, v108
	v_exp_f32_e32 v109, v109
	v_add_f32_e32 v235, v235, v105
	v_add_f32_e32 v234, v234, v106
	ds_read_b64_tr_b16 v[230:231], v151 offset:512
	ds_read_b64_tr_b16 v[232:233], v151 offset:2560
	s_waitcnt lgkmcnt(8)
	v_mfma_f32_32x32x16_bf16 v[64:79], v[206:209], v[112:115], v[64:79]
	v_exp_f32_e32 v110, v110
	v_exp_f32_e32 v111, v111
	v_add_f32_e32 v235, v235, v107
	v_add_f32_e32 v234, v234, v108
	ds_read_b64_tr_b16 v[238:239], v151 offset:1024
	ds_read_b64_tr_b16 v[240:241], v151 offset:3072
	s_waitcnt lgkmcnt(9)
	v_mfma_f32_32x32x16_bf16 v[80:95], v[210:213], v[124:127], 0
	v_add_f32_e32 v235, v235, v109
	v_add_f32_e32 v234, v234, v110
	v_add_f32_e32 v235, v235, v111
	v_cvt_pk_bf16_f32 v182, v104, v105
	v_cvt_pk_bf16_f32 v184, v108, v109
	ds_read_b64_tr_b16 v[242:243], v151 offset:1536
	ds_read_b64_tr_b16 v[244:245], v151 offset:3584
	s_waitcnt lgkmcnt(10)
	v_mfma_f32_32x32x16_bf16 v[80:95], v[214:217], v[120:123], v[80:95]
	v_cvt_pk_bf16_f32 v183, v106, v107
	v_cvt_pk_bf16_f32 v185, v110, v111
	v_permlane32_swap_b32_e32 v182, v184
	ds_read_b64_tr_b16 v[246:247], v151 offset:4096
	ds_read_b64_tr_b16 v[248:249], v151 offset:6144
	v_permlane32_swap_b32_e32 v183, v185
	s_waitcnt lgkmcnt(11)
	v_mfma_f32_32x32x16_bf16 v[80:95], v[218:221], v[116:119], v[80:95]
	v_exp_f32_e32 v162, v162
	v_exp_f32_e32 v163, v163
	ds_read_b64_tr_b16 v[250:251], v151 offset:4608
	ds_read_b64_tr_b16 v[252:253], v151 offset:6656
	s_waitcnt lgkmcnt(12)
	v_mfma_f32_32x32x16_bf16 v[80:95], v[222:225], v[112:115], v[80:95]
	v_exp_f32_e32 v164, v164
	v_exp_f32_e32 v165, v165
	v_add_f32_e32 v234, v234, v162
	ds_read_b64_tr_b16 v[152:153], v151 offset:5120
	ds_read_b64_tr_b16 v[154:155], v151 offset:7168
	s_waitcnt lgkmcnt(12)
	v_mfma_f32_32x32x16_bf16 v[48:63], v[178:181], v[226:229], v[48:63]
	v_exp_f32_e32 v166, v166
	v_exp_f32_e32 v167, v167
	v_add_f32_e32 v235, v235, v163
	v_add_f32_e32 v234, v234, v164
	ds_read_b64_tr_b16 v[226:227], v151 offset:5632
	ds_read_b64_tr_b16 v[228:229], v151 offset:7680
	s_waitcnt lgkmcnt(12)
	v_mfma_f32_32x32x16_bf16 v[32:47], v[178:181], v[230:233], v[32:47]
	v_exp_f32_e32 v168, v168
	v_exp_f32_e32 v169, v169
	v_add_f32_e32 v235, v235, v165
	v_add_f32_e32 v234, v234, v166
	ds_read_b64_tr_b16 v[230:231], v151 offset:8192
	ds_read_b64_tr_b16 v[232:233], v151 offset:10240
	s_waitcnt lgkmcnt(12)
	v_mfma_f32_32x32x16_bf16 v[16:31], v[178:181], v[238:241], v[16:31]
	v_add_f32_e32 v235, v235, v167
	v_add_f32_e32 v234, v234, v168
	v_add_f32_e32 v235, v235, v169
	v_cvt_pk_bf16_f32 v186, v162, v163
	v_cvt_pk_bf16_f32 v188, v166, v167
	ds_read_b64_tr_b16 v[238:239], v151 offset:8704
	ds_read_b64_tr_b16 v[240:241], v151 offset:10752
	s_waitcnt lgkmcnt(12)
	v_mfma_f32_32x32x16_bf16 v[0:15], v[178:181], v[242:245], v[0:15]
	v_cvt_pk_bf16_f32 v187, v164, v165
	v_cvt_pk_bf16_f32 v189, v168, v169
	v_permlane32_swap_b32_e32 v186, v188
	ds_read_b64_tr_b16 v[242:243], v151 offset:9216
	ds_read_b64_tr_b16 v[244:245], v151 offset:11264
	v_permlane32_swap_b32_e32 v187, v189
	s_waitcnt lgkmcnt(12)
	v_mfma_f32_32x32x16_bf16 v[48:63], v[182:185], v[246:249], v[48:63]
	v_exp_f32_e32 v170, v170
	v_exp_f32_e32 v171, v171
	ds_read_b64_tr_b16 v[246:247], v151 offset:9728
	ds_read_b64_tr_b16 v[248:249], v151 offset:11776
	s_waitcnt lgkmcnt(12)
	v_mfma_f32_32x32x16_bf16 v[32:47], v[182:185], v[250:253], v[32:47]
	v_exp_f32_e32 v172, v172
	v_exp_f32_e32 v173, v173
	v_add_f32_e32 v234, v234, v170
	ds_read_b64_tr_b16 v[250:251], v151 offset:12288
	ds_read_b64_tr_b16 v[252:253], v151 offset:14336
	s_waitcnt lgkmcnt(12)
	v_mfma_f32_32x32x16_bf16 v[16:31], v[182:185], v[152:155], v[16:31]
	v_exp_f32_e32 v174, v174
	v_exp_f32_e32 v175, v175
	v_add_f32_e32 v235, v235, v171
	v_add_f32_e32 v234, v234, v172
	ds_read_b64_tr_b16 v[152:153], v151 offset:12800
	ds_read_b64_tr_b16 v[154:155], v151 offset:14848
	s_waitcnt lgkmcnt(12)
	v_mfma_f32_32x32x16_bf16 v[0:15], v[182:185], v[226:229], v[0:15]
	v_exp_f32_e32 v176, v176
	v_exp_f32_e32 v177, v177
	v_add_f32_e32 v235, v235, v173
	v_add_f32_e32 v234, v234, v174
	ds_read_b64_tr_b16 v[226:227], v151 offset:13312
	ds_read_b64_tr_b16 v[228:229], v151 offset:15360
	s_waitcnt lgkmcnt(12)
	v_mfma_f32_32x32x16_bf16 v[48:63], v[186:189], v[230:233], v[48:63]
	v_add_f32_e32 v235, v235, v175
	v_add_f32_e32 v234, v234, v176
	v_add_f32_e32 v235, v235, v177
	v_cvt_pk_bf16_f32 v190, v170, v171
	v_cvt_pk_bf16_f32 v192, v174, v175
	ds_read_b64_tr_b16 v[230:231], v151 offset:13824
	ds_read_b64_tr_b16 v[232:233], v151 offset:15872
	s_waitcnt lgkmcnt(12)
	v_mfma_f32_32x32x16_bf16 v[32:47], v[186:189], v[238:241], v[32:47]
	s_add_i32 s62, s62, 0x4000
	s_cmp_ge_u32 s62, 0x14000
	s_cselect_b32 s69, 0x14000, 0
	s_sub_i32 s62, s62, s69
	v_add_u32_e32 v151, s62, v140
	v_cvt_pk_bf16_f32 v191, v172, v173
	v_cvt_pk_bf16_f32 v193, v176, v177
	v_permlane32_swap_b32_e32 v190, v192
	s_nop 0
	v_permlane32_swap_b32_e32 v191, v193
	s_waitcnt lgkmcnt(10)
	v_mfma_f32_32x32x16_bf16 v[16:31], v[186:189], v[242:245], v[16:31]
	v_exp_f32_e32 v64, v64
	v_exp_f32_e32 v65, v65
	ds_read_b128 v[194:197], v149 offset:49152
	s_waitcnt lgkmcnt(9)
	v_mfma_f32_32x32x16_bf16 v[0:15], v[186:189], v[246:249], v[0:15]
	v_exp_f32_e32 v66, v66
	v_exp_f32_e32 v67, v67
	v_add_f32_e32 v234, v234, v64
	ds_read_b128 v[198:201], v148 offset:49152
	s_waitcnt lgkmcnt(8)
	v_mfma_f32_32x32x16_bf16 v[48:63], v[190:193], v[250:253], v[48:63]
	v_exp_f32_e32 v68, v68
	v_exp_f32_e32 v69, v69
	v_add_f32_e32 v235, v235, v65
	v_add_f32_e32 v234, v234, v66
	ds_read_b128 v[202:205], v143 offset:49152
	s_waitcnt lgkmcnt(7)
	v_mfma_f32_32x32x16_bf16 v[32:47], v[190:193], v[152:155], v[32:47]
	v_exp_f32_e32 v70, v70
	v_exp_f32_e32 v71, v71
	v_add_f32_e32 v235, v235, v67
	v_add_f32_e32 v234, v234, v68
	ds_read_b128 v[206:209], v141 offset:49152
	s_waitcnt lgkmcnt(6)
	v_mfma_f32_32x32x16_bf16 v[16:31], v[190:193], v[226:229], v[16:31]
	v_add_f32_e32 v235, v235, v69
	v_add_f32_e32 v234, v234, v70
	v_add_f32_e32 v235, v235, v71
	v_cvt_pk_bf16_f32 v178, v64, v65
	v_cvt_pk_bf16_f32 v180, v68, v69
	ds_read_b128 v[210:213], v149 offset:57344
	s_waitcnt lgkmcnt(5)
	v_mfma_f32_32x32x16_bf16 v[0:15], v[190:193], v[230:233], v[0:15]
	v_cvt_pk_bf16_f32 v179, v66, v67
	v_cvt_pk_bf16_f32 v181, v70, v71
	v_permlane32_swap_b32_e32 v178, v180
	ds_read_b128 v[214:217], v148 offset:57344
	v_permlane32_swap_b32_e32 v179, v181
	s_waitcnt lgkmcnt(5)
	v_mfma_f32_32x32x16_bf16 v[96:111], v[194:197], v[124:127], 0
	v_exp_f32_e32 v72, v72
	v_exp_f32_e32 v73, v73
	ds_read_b128 v[218:221], v143 offset:57344
	s_waitcnt lgkmcnt(5)
	v_mfma_f32_32x32x16_bf16 v[96:111], v[198:201], v[120:123], v[96:111]
	v_exp_f32_e32 v74, v74
	v_exp_f32_e32 v75, v75
	v_add_f32_e32 v234, v234, v72
	ds_read_b128 v[222:225], v141 offset:57344
	ds_read_b64_tr_b16 v[226:227], v151 offset:0
	ds_read_b64_tr_b16 v[228:229], v151 offset:2048
	s_waitcnt lgkmcnt(7)
	v_mfma_f32_32x32x16_bf16 v[96:111], v[202:205], v[116:119], v[96:111]
	v_exp_f32_e32 v76, v76
	v_exp_f32_e32 v77, v77
	v_add_f32_e32 v235, v235, v73
	v_add_f32_e32 v234, v234, v74
	ds_read_b64_tr_b16 v[230:231], v151 offset:512
	ds_read_b64_tr_b16 v[232:233], v151 offset:2560
	s_waitcnt lgkmcnt(8)
	v_mfma_f32_32x32x16_bf16 v[96:111], v[206:209], v[112:115], v[96:111]
	v_exp_f32_e32 v78, v78
	v_exp_f32_e32 v79, v79
	v_add_f32_e32 v235, v235, v75
	v_add_f32_e32 v234, v234, v76
	ds_read_b64_tr_b16 v[238:239], v151 offset:1024
	ds_read_b64_tr_b16 v[240:241], v151 offset:3072
	s_waitcnt lgkmcnt(9)
	v_mfma_f32_32x32x16_bf16 v[162:177], v[210:213], v[124:127], 0
	v_add_f32_e32 v235, v235, v77
	v_add_f32_e32 v234, v234, v78
	v_add_f32_e32 v235, v235, v79
	v_cvt_pk_bf16_f32 v182, v72, v73
	v_cvt_pk_bf16_f32 v184, v76, v77
	ds_read_b64_tr_b16 v[242:243], v151 offset:1536
	ds_read_b64_tr_b16 v[244:245], v151 offset:3584
	s_waitcnt lgkmcnt(10)
	v_mfma_f32_32x32x16_bf16 v[162:177], v[214:217], v[120:123], v[162:177]
	v_cvt_pk_bf16_f32 v183, v74, v75
	v_cvt_pk_bf16_f32 v185, v78, v79
	v_permlane32_swap_b32_e32 v182, v184
	ds_read_b64_tr_b16 v[246:247], v151 offset:4096
	ds_read_b64_tr_b16 v[248:249], v151 offset:6144
	v_permlane32_swap_b32_e32 v183, v185
	s_waitcnt lgkmcnt(11)
	v_mfma_f32_32x32x16_bf16 v[162:177], v[218:221], v[116:119], v[162:177]
	v_exp_f32_e32 v80, v80
	v_exp_f32_e32 v81, v81
	ds_read_b64_tr_b16 v[250:251], v151 offset:4608
	ds_read_b64_tr_b16 v[252:253], v151 offset:6656
	s_waitcnt lgkmcnt(12)
	v_mfma_f32_32x32x16_bf16 v[162:177], v[222:225], v[112:115], v[162:177]
	v_exp_f32_e32 v82, v82
	v_exp_f32_e32 v83, v83
	v_add_f32_e32 v234, v234, v80
	ds_read_b64_tr_b16 v[152:153], v151 offset:5120
	ds_read_b64_tr_b16 v[154:155], v151 offset:7168
	s_waitcnt lgkmcnt(12)
	v_mfma_f32_32x32x16_bf16 v[48:63], v[178:181], v[226:229], v[48:63]
	v_exp_f32_e32 v84, v84
	v_exp_f32_e32 v85, v85
	v_add_f32_e32 v235, v235, v81
	v_add_f32_e32 v234, v234, v82
	ds_read_b64_tr_b16 v[226:227], v151 offset:5632
	ds_read_b64_tr_b16 v[228:229], v151 offset:7680
	s_waitcnt lgkmcnt(12)
	v_mfma_f32_32x32x16_bf16 v[32:47], v[178:181], v[230:233], v[32:47]
	v_exp_f32_e32 v86, v86
	v_exp_f32_e32 v87, v87
	v_add_f32_e32 v235, v235, v83
	v_add_f32_e32 v234, v234, v84
	ds_read_b64_tr_b16 v[230:231], v151 offset:8192
	ds_read_b64_tr_b16 v[232:233], v151 offset:10240
	s_waitcnt lgkmcnt(12)
	v_mfma_f32_32x32x16_bf16 v[16:31], v[178:181], v[238:241], v[16:31]
	v_add_f32_e32 v235, v235, v85
	v_add_f32_e32 v234, v234, v86
	v_add_f32_e32 v235, v235, v87
	v_cvt_pk_bf16_f32 v186, v80, v81
	v_cvt_pk_bf16_f32 v188, v84, v85
	ds_read_b64_tr_b16 v[238:239], v151 offset:8704
	ds_read_b64_tr_b16 v[240:241], v151 offset:10752
	s_waitcnt lgkmcnt(12)
	v_mfma_f32_32x32x16_bf16 v[0:15], v[178:181], v[242:245], v[0:15]
	v_cvt_pk_bf16_f32 v187, v82, v83
	v_cvt_pk_bf16_f32 v189, v86, v87
	v_permlane32_swap_b32_e32 v186, v188
	ds_read_b64_tr_b16 v[242:243], v151 offset:9216
	ds_read_b64_tr_b16 v[244:245], v151 offset:11264
	v_permlane32_swap_b32_e32 v187, v189
	s_waitcnt lgkmcnt(12)
	v_mfma_f32_32x32x16_bf16 v[48:63], v[182:185], v[246:249], v[48:63]
	v_exp_f32_e32 v88, v88
	v_exp_f32_e32 v89, v89
	ds_read_b64_tr_b16 v[246:247], v151 offset:9728
	ds_read_b64_tr_b16 v[248:249], v151 offset:11776
	s_waitcnt lgkmcnt(12)
	v_mfma_f32_32x32x16_bf16 v[32:47], v[182:185], v[250:253], v[32:47]
	v_exp_f32_e32 v90, v90
	v_exp_f32_e32 v91, v91
	v_add_f32_e32 v234, v234, v88
	ds_read_b64_tr_b16 v[250:251], v151 offset:12288
	ds_read_b64_tr_b16 v[252:253], v151 offset:14336
	s_waitcnt lgkmcnt(12)
	v_mfma_f32_32x32x16_bf16 v[16:31], v[182:185], v[152:155], v[16:31]
	v_exp_f32_e32 v92, v92
	v_exp_f32_e32 v93, v93
	v_add_f32_e32 v235, v235, v89
	v_add_f32_e32 v234, v234, v90
	ds_read_b64_tr_b16 v[152:153], v151 offset:12800
	ds_read_b64_tr_b16 v[154:155], v151 offset:14848
	s_waitcnt lgkmcnt(12)
	v_mfma_f32_32x32x16_bf16 v[0:15], v[182:185], v[226:229], v[0:15]
	v_exp_f32_e32 v94, v94
	v_exp_f32_e32 v95, v95
	v_add_f32_e32 v235, v235, v91
	v_add_f32_e32 v234, v234, v92
	ds_read_b64_tr_b16 v[226:227], v151 offset:13312
	ds_read_b64_tr_b16 v[228:229], v151 offset:15360
	s_waitcnt lgkmcnt(12)
	v_mfma_f32_32x32x16_bf16 v[48:63], v[186:189], v[230:233], v[48:63]
	v_add_f32_e32 v235, v235, v93
	v_add_f32_e32 v234, v234, v94
	v_add_f32_e32 v235, v235, v95
	v_cvt_pk_bf16_f32 v190, v88, v89
	v_cvt_pk_bf16_f32 v192, v92, v93
	ds_read_b64_tr_b16 v[230:231], v151 offset:13824
	ds_read_b64_tr_b16 v[232:233], v151 offset:15872
	s_waitcnt lgkmcnt(12)
	v_mfma_f32_32x32x16_bf16 v[32:47], v[186:189], v[238:241], v[32:47]
	s_waitcnt vmcnt(0)
	s_barrier
	s_add_i32 s63, s62, 0xc000
	s_cmp_ge_u32 s63, 0x14000
	s_cselect_b32 s69, 0x14000, 0
	s_sub_i32 s63, s63, s69
	s_add_i32 s68, s62, 0x10000
	s_cmp_ge_u32 s68, 0x14000
	s_cselect_b32 s69, 0x14000, 0
	s_sub_i32 s68, s68, s69
	s_add_i32 s62, s62, 0x4000
	s_cmp_ge_u32 s62, 0x14000
	s_cselect_b32 s69, 0x14000, 0
	s_sub_i32 s62, s62, s69
	v_add_u32_e32 v151, s62, v140
	v_cvt_pk_bf16_f32 v191, v90, v91
	v_cvt_pk_bf16_f32 v193, v94, v95
	v_permlane32_swap_b32_e32 v190, v192
	s_nop 0
	v_permlane32_swap_b32_e32 v191, v193
	s_add_i32 m0, s41, s63
	v_lshl_add_u64 v[146:147], v[132:133], 0, s[42:43]
	global_load_lds_dwordx4 v[146:147], off
	s_waitcnt lgkmcnt(10)
	v_mfma_f32_32x32x16_bf16 v[16:31], v[186:189], v[242:245], v[16:31]
	v_exp_f32_e32 v96, v96
	v_exp_f32_e32 v97, v97
	ds_read_b128 v[194:197], v149 offset:0
	s_add_i32 m0, s71, s63
	v_lshl_add_u64 v[254:255], v[132:133], 0, s[46:47]
	global_load_lds_dwordx4 v[254:255], off
	s_waitcnt lgkmcnt(9)
	v_mfma_f32_32x32x16_bf16 v[0:15], v[186:189], v[246:249], v[0:15]
	v_exp_f32_e32 v98, v98
	v_exp_f32_e32 v99, v99
	v_add_f32_e32 v234, v234, v96
	ds_read_b128 v[198:201], v148 offset:0
	s_add_i32 m0, s40, 0x8000
	v_lshl_add_u64 v[146:147], v[134:135], 0, s[84:85]
	global_load_lds_dwordx4 v[146:147], off
	s_waitcnt lgkmcnt(8)
	v_mfma_f32_32x32x16_bf16 v[48:63], v[190:193], v[250:253], v[48:63]
	v_exp_f32_e32 v100, v100
	v_exp_f32_e32 v101, v101
	v_add_f32_e32 v235, v235, v97
	v_add_f32_e32 v234, v234, v98
	ds_read_b128 v[202:205], v143 offset:0
	s_add_i32 m0, s40, 0xa000
	v_lshl_add_u64 v[254:255], v[134:135], 0, s[86:87]
	global_load_lds_dwordx4 v[254:255], off
	s_waitcnt lgkmcnt(7)
	v_mfma_f32_32x32x16_bf16 v[32:47], v[190:193], v[152:155], v[32:47]
	v_exp_f32_e32 v102, v102
	v_exp_f32_e32 v103, v103
	v_add_f32_e32 v235, v235, v99
	v_add_f32_e32 v234, v234, v100
	ds_read_b128 v[206:209], v141 offset:0
	s_add_i32 m0, s41, s68
	v_lshl_add_u64 v[146:147], v[132:133], 0, s[88:89]
	global_load_lds_dwordx4 v[146:147], off
	s_waitcnt lgkmcnt(6)
	v_mfma_f32_32x32x16_bf16 v[16:31], v[190:193], v[226:229], v[16:31]
	v_add_f32_e32 v235, v235, v101
	v_add_f32_e32 v234, v234, v102
	v_add_f32_e32 v235, v235, v103
	v_cvt_pk_bf16_f32 v178, v96, v97
	v_cvt_pk_bf16_f32 v180, v100, v101
	ds_read_b128 v[210:213], v149 offset:8192
	s_add_i32 m0, s71, s68
	v_lshl_add_u64 v[254:255], v[132:133], 0, s[90:91]
	global_load_lds_dwordx4 v[254:255], off
	s_waitcnt lgkmcnt(5)
	v_mfma_f32_32x32x16_bf16 v[0:15], v[190:193], v[230:233], v[0:15]
	v_cvt_pk_bf16_f32 v179, v98, v99
	v_cvt_pk_bf16_f32 v181, v102, v103
	v_permlane32_swap_b32_e32 v178, v180
	ds_read_b128 v[214:217], v148 offset:8192
	v_permlane32_swap_b32_e32 v179, v181
	s_add_i32 m0, s40, 0xc000
	v_lshl_add_u64 v[146:147], v[134:135], 0, s[92:93]
	global_load_lds_dwordx4 v[146:147], off
	s_add_i32 m0, s40, 0xe000
	v_lshl_add_u64 v[254:255], v[134:135], 0, s[94:95]
	global_load_lds_dwordx4 v[254:255], off
	v_lshl_add_u64 v[132:133], v[132:133], 0, s[12:13]
	v_lshl_add_u64 v[134:135], v[134:135], 0, s[12:13]
	s_waitcnt lgkmcnt(5)
	v_mfma_f32_32x32x16_bf16 v[64:79], v[194:197], v[124:127], 0
	v_exp_f32_e32 v104, v104
	v_exp_f32_e32 v105, v105
	ds_read_b128 v[218:221], v143 offset:8192
	s_waitcnt lgkmcnt(5)
	v_mfma_f32_32x32x16_bf16 v[64:79], v[198:201], v[120:123], v[64:79]
	v_exp_f32_e32 v106, v106
	v_exp_f32_e32 v107, v107
	v_add_f32_e32 v234, v234, v104
	ds_read_b128 v[222:225], v141 offset:8192
	ds_read_b64_tr_b16 v[226:227], v151 offset:0
	ds_read_b64_tr_b16 v[228:229], v151 offset:2048
	s_waitcnt lgkmcnt(7)
	v_mfma_f32_32x32x16_bf16 v[64:79], v[202:205], v[116:119], v[64:79]
	v_exp_f32_e32 v108, v108
	v_exp_f32_e32 v109, v109
	v_add_f32_e32 v235, v235, v105
	v_add_f32_e32 v234, v234, v106
	ds_read_b64_tr_b16 v[230:231], v151 offset:512
	ds_read_b64_tr_b16 v[232:233], v151 offset:2560
	s_waitcnt lgkmcnt(8)
	v_mfma_f32_32x32x16_bf16 v[64:79], v[206:209], v[112:115], v[64:79]
	v_exp_f32_e32 v110, v110
	v_exp_f32_e32 v111, v111
	v_add_f32_e32 v235, v235, v107
	v_add_f32_e32 v234, v234, v108
	ds_read_b64_tr_b16 v[238:239], v151 offset:1024
	ds_read_b64_tr_b16 v[240:241], v151 offset:3072
	s_waitcnt lgkmcnt(9)
	v_mfma_f32_32x32x16_bf16 v[80:95], v[210:213], v[124:127], 0
	v_add_f32_e32 v235, v235, v109
	v_add_f32_e32 v234, v234, v110
	v_add_f32_e32 v235, v235, v111
	v_cvt_pk_bf16_f32 v182, v104, v105
	v_cvt_pk_bf16_f32 v184, v108, v109
	ds_read_b64_tr_b16 v[242:243], v151 offset:1536
	ds_read_b64_tr_b16 v[244:245], v151 offset:3584
	s_waitcnt lgkmcnt(10)
	v_mfma_f32_32x32x16_bf16 v[80:95], v[214:217], v[120:123], v[80:95]
	v_cvt_pk_bf16_f32 v183, v106, v107
	v_cvt_pk_bf16_f32 v185, v110, v111
	v_permlane32_swap_b32_e32 v182, v184
	ds_read_b64_tr_b16 v[246:247], v151 offset:4096
	ds_read_b64_tr_b16 v[248:249], v151 offset:6144
	v_permlane32_swap_b32_e32 v183, v185
	s_waitcnt lgkmcnt(11)
	v_mfma_f32_32x32x16_bf16 v[80:95], v[218:221], v[116:119], v[80:95]
	v_exp_f32_e32 v162, v162
	v_exp_f32_e32 v163, v163
	ds_read_b64_tr_b16 v[250:251], v151 offset:4608
	ds_read_b64_tr_b16 v[252:253], v151 offset:6656
	s_waitcnt lgkmcnt(12)
	v_mfma_f32_32x32x16_bf16 v[80:95], v[222:225], v[112:115], v[80:95]
	v_exp_f32_e32 v164, v164
	v_exp_f32_e32 v165, v165
	v_add_f32_e32 v234, v234, v162
	ds_read_b64_tr_b16 v[152:153], v151 offset:5120
	ds_read_b64_tr_b16 v[154:155], v151 offset:7168
	s_waitcnt lgkmcnt(12)
	v_mfma_f32_32x32x16_bf16 v[48:63], v[178:181], v[226:229], v[48:63]
	v_exp_f32_e32 v166, v166
	v_exp_f32_e32 v167, v167
	v_add_f32_e32 v235, v235, v163
	v_add_f32_e32 v234, v234, v164
	ds_read_b64_tr_b16 v[226:227], v151 offset:5632
	ds_read_b64_tr_b16 v[228:229], v151 offset:7680
	s_waitcnt lgkmcnt(12)
	v_mfma_f32_32x32x16_bf16 v[32:47], v[178:181], v[230:233], v[32:47]
	v_exp_f32_e32 v168, v168
	v_exp_f32_e32 v169, v169
	v_add_f32_e32 v235, v235, v165
	v_add_f32_e32 v234, v234, v166
	ds_read_b64_tr_b16 v[230:231], v151 offset:8192
	ds_read_b64_tr_b16 v[232:233], v151 offset:10240
	s_waitcnt lgkmcnt(12)
	v_mfma_f32_32x32x16_bf16 v[16:31], v[178:181], v[238:241], v[16:31]
	v_add_f32_e32 v235, v235, v167
	v_add_f32_e32 v234, v234, v168
	v_add_f32_e32 v235, v235, v169
	v_cvt_pk_bf16_f32 v186, v162, v163
	v_cvt_pk_bf16_f32 v188, v166, v167
	ds_read_b64_tr_b16 v[238:239], v151 offset:8704
	ds_read_b64_tr_b16 v[240:241], v151 offset:10752
	s_waitcnt lgkmcnt(12)
	v_mfma_f32_32x32x16_bf16 v[0:15], v[178:181], v[242:245], v[0:15]
	v_cvt_pk_bf16_f32 v187, v164, v165
	v_cvt_pk_bf16_f32 v189, v168, v169
	v_permlane32_swap_b32_e32 v186, v188
	ds_read_b64_tr_b16 v[242:243], v151 offset:9216
	ds_read_b64_tr_b16 v[244:245], v151 offset:11264
	v_permlane32_swap_b32_e32 v187, v189
	s_waitcnt lgkmcnt(12)
	v_mfma_f32_32x32x16_bf16 v[48:63], v[182:185], v[246:249], v[48:63]
	v_exp_f32_e32 v170, v170
	v_exp_f32_e32 v171, v171
	ds_read_b64_tr_b16 v[246:247], v151 offset:9728
	ds_read_b64_tr_b16 v[248:249], v151 offset:11776
	s_waitcnt lgkmcnt(12)
	v_mfma_f32_32x32x16_bf16 v[32:47], v[182:185], v[250:253], v[32:47]
	v_exp_f32_e32 v172, v172
	v_exp_f32_e32 v173, v173
	v_add_f32_e32 v234, v234, v170
	ds_read_b64_tr_b16 v[250:251], v151 offset:12288
	ds_read_b64_tr_b16 v[252:253], v151 offset:14336
	s_waitcnt lgkmcnt(12)
	v_mfma_f32_32x32x16_bf16 v[16:31], v[182:185], v[152:155], v[16:31]
	v_exp_f32_e32 v174, v174
	v_exp_f32_e32 v175, v175
	v_add_f32_e32 v235, v235, v171
	v_add_f32_e32 v234, v234, v172
	ds_read_b64_tr_b16 v[152:153], v151 offset:12800
	ds_read_b64_tr_b16 v[154:155], v151 offset:14848
	s_waitcnt lgkmcnt(12)
	v_mfma_f32_32x32x16_bf16 v[0:15], v[182:185], v[226:229], v[0:15]
	v_exp_f32_e32 v176, v176
	v_exp_f32_e32 v177, v177
	v_add_f32_e32 v235, v235, v173
	v_add_f32_e32 v234, v234, v174
	ds_read_b64_tr_b16 v[226:227], v151 offset:13312
	ds_read_b64_tr_b16 v[228:229], v151 offset:15360
	s_waitcnt lgkmcnt(12)
	v_mfma_f32_32x32x16_bf16 v[48:63], v[186:189], v[230:233], v[48:63]
	v_add_f32_e32 v235, v235, v175
	v_add_f32_e32 v234, v234, v176
	v_add_f32_e32 v235, v235, v177
	v_cvt_pk_bf16_f32 v190, v170, v171
	v_cvt_pk_bf16_f32 v192, v174, v175
	ds_read_b64_tr_b16 v[230:231], v151 offset:13824
	ds_read_b64_tr_b16 v[232:233], v151 offset:15872
	s_waitcnt lgkmcnt(12)
	v_mfma_f32_32x32x16_bf16 v[32:47], v[186:189], v[238:241], v[32:47]
	s_add_i32 s62, s62, 0x4000
	s_cmp_ge_u32 s62, 0x14000
	s_cselect_b32 s69, 0x14000, 0
	s_sub_i32 s62, s62, s69
	v_add_u32_e32 v151, s62, v140
	v_cvt_pk_bf16_f32 v191, v172, v173
	v_cvt_pk_bf16_f32 v193, v176, v177
	v_permlane32_swap_b32_e32 v190, v192
	s_nop 0
	v_permlane32_swap_b32_e32 v191, v193
	s_waitcnt lgkmcnt(10)
	v_mfma_f32_32x32x16_bf16 v[16:31], v[186:189], v[242:245], v[16:31]
	v_exp_f32_e32 v64, v64
	v_exp_f32_e32 v65, v65
	ds_read_b128 v[194:197], v149 offset:16384
	s_waitcnt lgkmcnt(9)
	v_mfma_f32_32x32x16_bf16 v[0:15], v[186:189], v[246:249], v[0:15]
	v_exp_f32_e32 v66, v66
	v_exp_f32_e32 v67, v67
	v_add_f32_e32 v234, v234, v64
	ds_read_b128 v[198:201], v148 offset:16384
	s_waitcnt lgkmcnt(8)
	v_mfma_f32_32x32x16_bf16 v[48:63], v[190:193], v[250:253], v[48:63]
	v_exp_f32_e32 v68, v68
	v_exp_f32_e32 v69, v69
	v_add_f32_e32 v235, v235, v65
	v_add_f32_e32 v234, v234, v66
	ds_read_b128 v[202:205], v143 offset:16384
	s_waitcnt lgkmcnt(7)
	v_mfma_f32_32x32x16_bf16 v[32:47], v[190:193], v[152:155], v[32:47]
	v_exp_f32_e32 v70, v70
	v_exp_f32_e32 v71, v71
	v_add_f32_e32 v235, v235, v67
	v_add_f32_e32 v234, v234, v68
	ds_read_b128 v[206:209], v141 offset:16384
	s_waitcnt lgkmcnt(6)
	v_mfma_f32_32x32x16_bf16 v[16:31], v[190:193], v[226:229], v[16:31]
	v_add_f32_e32 v235, v235, v69
	v_add_f32_e32 v234, v234, v70
	v_add_f32_e32 v235, v235, v71
	v_cvt_pk_bf16_f32 v178, v64, v65
	v_cvt_pk_bf16_f32 v180, v68, v69
	ds_read_b128 v[210:213], v149 offset:24576
	s_waitcnt lgkmcnt(5)
	v_mfma_f32_32x32x16_bf16 v[0:15], v[190:193], v[230:233], v[0:15]
	v_cvt_pk_bf16_f32 v179, v66, v67
	v_cvt_pk_bf16_f32 v181, v70, v71
	v_permlane32_swap_b32_e32 v178, v180
	ds_read_b128 v[214:217], v148 offset:24576
	v_permlane32_swap_b32_e32 v179, v181
	s_sub_i32 s70, s70, 1
	s_cmp_lg_u32 s70, 0
	s_cbranch_scc1 .Lda_loop
	s_waitcnt lgkmcnt(5)
	v_mfma_f32_32x32x16_bf16 v[96:111], v[194:197], v[124:127], 0
	v_exp_f32_e32 v72, v72
	v_exp_f32_e32 v73, v73
	ds_read_b128 v[218:221], v143 offset:24576
	s_waitcnt lgkmcnt(5)
	v_mfma_f32_32x32x16_bf16 v[96:111], v[198:201], v[120:123], v[96:111]
	v_exp_f32_e32 v74, v74
	v_exp_f32_e32 v75, v75
	v_add_f32_e32 v234, v234, v72
	ds_read_b128 v[222:225], v141 offset:24576
	ds_read_b64_tr_b16 v[226:227], v151 offset:0
	ds_read_b64_tr_b16 v[228:229], v151 offset:2048
	s_waitcnt lgkmcnt(7)
	v_mfma_f32_32x32x16_bf16 v[96:111], v[202:205], v[116:119], v[96:111]
	v_exp_f32_e32 v76, v76
	v_exp_f32_e32 v77, v77
	v_add_f32_e32 v235, v235, v73
	v_add_f32_e32 v234, v234, v74
	ds_read_b64_tr_b16 v[230:231], v151 offset:512
	ds_read_b64_tr_b16 v[232:233], v151 offset:2560
	s_waitcnt lgkmcnt(8)
	v_mfma_f32_32x32x16_bf16 v[96:111], v[206:209], v[112:115], v[96:111]
	v_exp_f32_e32 v78, v78
	v_exp_f32_e32 v79, v79
	v_add_f32_e32 v235, v235, v75
	v_add_f32_e32 v234, v234, v76
	ds_read_b64_tr_b16 v[238:239], v151 offset:1024
	ds_read_b64_tr_b16 v[240:241], v151 offset:3072
	s_waitcnt lgkmcnt(9)
	v_mfma_f32_32x32x16_bf16 v[162:177], v[210:213], v[124:127], 0
	v_add_f32_e32 v235, v235, v77
	v_add_f32_e32 v234, v234, v78
	v_add_f32_e32 v235, v235, v79
	v_cvt_pk_bf16_f32 v182, v72, v73
	v_cvt_pk_bf16_f32 v184, v76, v77
	ds_read_b64_tr_b16 v[242:243], v151 offset:1536
	ds_read_b64_tr_b16 v[244:245], v151 offset:3584
	s_waitcnt lgkmcnt(10)
	v_mfma_f32_32x32x16_bf16 v[162:177], v[214:217], v[120:123], v[162:177]
	v_cvt_pk_bf16_f32 v183, v74, v75
	v_cvt_pk_bf16_f32 v185, v78, v79
	v_permlane32_swap_b32_e32 v182, v184
	ds_read_b64_tr_b16 v[246:247], v151 offset:4096
	ds_read_b64_tr_b16 v[248:249], v151 offset:6144
	v_permlane32_swap_b32_e32 v183, v185
	s_waitcnt lgkmcnt(11)
	v_mfma_f32_32x32x16_bf16 v[162:177], v[218:221], v[116:119], v[162:177]
	v_exp_f32_e32 v80, v80
	v_exp_f32_e32 v81, v81
	ds_read_b64_tr_b16 v[250:251], v151 offset:4608
	ds_read_b64_tr_b16 v[252:253], v151 offset:6656
	s_waitcnt lgkmcnt(12)
	v_mfma_f32_32x32x16_bf16 v[162:177], v[222:225], v[112:115], v[162:177]
	v_exp_f32_e32 v82, v82
	v_exp_f32_e32 v83, v83
	v_add_f32_e32 v234, v234, v80
	ds_read_b64_tr_b16 v[152:153], v151 offset:5120
	ds_read_b64_tr_b16 v[154:155], v151 offset:7168
	s_waitcnt lgkmcnt(12)
	v_mfma_f32_32x32x16_bf16 v[48:63], v[178:181], v[226:229], v[48:63]
	v_exp_f32_e32 v84, v84
	v_exp_f32_e32 v85, v85
	v_add_f32_e32 v235, v235, v81
	v_add_f32_e32 v234, v234, v82
	ds_read_b64_tr_b16 v[226:227], v151 offset:5632
	ds_read_b64_tr_b16 v[228:229], v151 offset:7680
	s_waitcnt lgkmcnt(12)
	v_mfma_f32_32x32x16_bf16 v[32:47], v[178:181], v[230:233], v[32:47]
	v_exp_f32_e32 v86, v86
	v_exp_f32_e32 v87, v87
	v_add_f32_e32 v235, v235, v83
	v_add_f32_e32 v234, v234, v84
	ds_read_b64_tr_b16 v[230:231], v151 offset:8192
	ds_read_b64_tr_b16 v[232:233], v151 offset:10240
	s_waitcnt lgkmcnt(12)
	v_mfma_f32_32x32x16_bf16 v[16:31], v[178:181], v[238:241], v[16:31]
	v_add_f32_e32 v235, v235, v85
	v_add_f32_e32 v234, v234, v86
	v_add_f32_e32 v235, v235, v87
	v_cvt_pk_bf16_f32 v186, v80, v81
	v_cvt_pk_bf16_f32 v188, v84, v85
	ds_read_b64_tr_b16 v[238:239], v151 offset:8704
	ds_read_b64_tr_b16 v[240:241], v151 offset:10752
	s_waitcnt lgkmcnt(12)
	v_mfma_f32_32x32x16_bf16 v[0:15], v[178:181], v[242:245], v[0:15]
	v_cvt_pk_bf16_f32 v187, v82, v83
	v_cvt_pk_bf16_f32 v189, v86, v87
	v_permlane32_swap_b32_e32 v186, v188
	ds_read_b64_tr_b16 v[242:243], v151 offset:9216
	ds_read_b64_tr_b16 v[244:245], v151 offset:11264
	v_permlane32_swap_b32_e32 v187, v189
	s_waitcnt lgkmcnt(12)
	v_mfma_f32_32x32x16_bf16 v[48:63], v[182:185], v[246:249], v[48:63]
	v_exp_f32_e32 v88, v88
	v_exp_f32_e32 v89, v89
	ds_read_b64_tr_b16 v[246:247], v151 offset:9728
	ds_read_b64_tr_b16 v[248:249], v151 offset:11776
	s_waitcnt lgkmcnt(12)
	v_mfma_f32_32x32x16_bf16 v[32:47], v[182:185], v[250:253], v[32:47]
	v_exp_f32_e32 v90, v90
	v_exp_f32_e32 v91, v91
	v_add_f32_e32 v234, v234, v88
	ds_read_b64_tr_b16 v[250:251], v151 offset:12288
	ds_read_b64_tr_b16 v[252:253], v151 offset:14336
	s_waitcnt lgkmcnt(12)
	v_mfma_f32_32x32x16_bf16 v[16:31], v[182:185], v[152:155], v[16:31]
	v_exp_f32_e32 v92, v92
	v_exp_f32_e32 v93, v93
	v_add_f32_e32 v235, v235, v89
	v_add_f32_e32 v234, v234, v90
	ds_read_b64_tr_b16 v[152:153], v151 offset:12800
	ds_read_b64_tr_b16 v[154:155], v151 offset:14848
	s_waitcnt lgkmcnt(12)
	v_mfma_f32_32x32x16_bf16 v[0:15], v[182:185], v[226:229], v[0:15]
	v_exp_f32_e32 v94, v94
	v_exp_f32_e32 v95, v95
	v_add_f32_e32 v235, v235, v91
	v_add_f32_e32 v234, v234, v92
	ds_read_b64_tr_b16 v[226:227], v151 offset:13312
	ds_read_b64_tr_b16 v[228:229], v151 offset:15360
	s_waitcnt lgkmcnt(12)
	v_mfma_f32_32x32x16_bf16 v[48:63], v[186:189], v[230:233], v[48:63]
	v_add_f32_e32 v235, v235, v93
	v_add_f32_e32 v234, v234, v94
	v_add_f32_e32 v235, v235, v95
	v_cvt_pk_bf16_f32 v190, v88, v89
	v_cvt_pk_bf16_f32 v192, v92, v93
	ds_read_b64_tr_b16 v[230:231], v151 offset:13824
	ds_read_b64_tr_b16 v[232:233], v151 offset:15872
	s_waitcnt lgkmcnt(12)
	v_mfma_f32_32x32x16_bf16 v[32:47], v[186:189], v[238:241], v[32:47]
	s_waitcnt vmcnt(0)
	s_barrier
	s_add_i32 s63, s62, 0xc000
	s_cmp_ge_u32 s63, 0x14000
	s_cselect_b32 s69, 0x14000, 0
	s_sub_i32 s63, s63, s69
	s_add_i32 s62, s62, 0x4000
	s_cmp_ge_u32 s62, 0x14000
	s_cselect_b32 s69, 0x14000, 0
	s_sub_i32 s62, s62, s69
	v_add_u32_e32 v151, s62, v140
	v_cvt_pk_bf16_f32 v191, v90, v91
	v_cvt_pk_bf16_f32 v193, v94, v95
	v_permlane32_swap_b32_e32 v190, v192
	s_nop 0
	v_permlane32_swap_b32_e32 v191, v193
	s_add_i32 m0, s41, s63
	v_lshl_add_u64 v[146:147], v[132:133], 0, s[42:43]
	global_load_lds_dwordx4 v[146:147], off
	s_waitcnt lgkmcnt(10)
	v_mfma_f32_32x32x16_bf16 v[16:31], v[186:189], v[242:245], v[16:31]
	v_exp_f32_e32 v96, v96
	v_exp_f32_e32 v97, v97
	ds_read_b128 v[194:197], v149 offset:32768
	s_add_i32 m0, s71, s63
	v_lshl_add_u64 v[254:255], v[132:133], 0, s[46:47]
	global_load_lds_dwordx4 v[254:255], off
	s_waitcnt lgkmcnt(9)
	v_mfma_f32_32x32x16_bf16 v[0:15], v[186:189], v[246:249], v[0:15]
	v_exp_f32_e32 v98, v98
	v_exp_f32_e32 v99, v99
	v_add_f32_e32 v234, v234, v96
	ds_read_b128 v[198:201], v148 offset:32768
	s_waitcnt lgkmcnt(8)
	v_mfma_f32_32x32x16_bf16 v[48:63], v[190:193], v[250:253], v[48:63]
	v_exp_f32_e32 v100, v100
	v_exp_f32_e32 v101, v101
	v_add_f32_e32 v235, v235, v97
	v_add_f32_e32 v234, v234, v98
	ds_read_b128 v[202:205], v143 offset:32768
	s_waitcnt lgkmcnt(7)
	v_mfma_f32_32x32x16_bf16 v[32:47], v[190:193], v[152:155], v[32:47]
	v_exp_f32_e32 v102, v102
	v_exp_f32_e32 v103, v103
	v_add_f32_e32 v235, v235, v99
	v_add_f32_e32 v234, v234, v100
	ds_read_b128 v[206:209], v141 offset:32768
	s_waitcnt lgkmcnt(6)
	v_mfma_f32_32x32x16_bf16 v[16:31], v[190:193], v[226:229], v[16:31]
	v_add_f32_e32 v235, v235, v101
	v_add_f32_e32 v234, v234, v102
	v_add_f32_e32 v235, v235, v103
	v_cvt_pk_bf16_f32 v178, v96, v97
	v_cvt_pk_bf16_f32 v180, v100, v101
	ds_read_b128 v[210:213], v149 offset:40960
	s_waitcnt lgkmcnt(5)
	v_mfma_f32_32x32x16_bf16 v[0:15], v[190:193], v[230:233], v[0:15]
	v_cvt_pk_bf16_f32 v179, v98, v99
	v_cvt_pk_bf16_f32 v181, v102, v103
	v_permlane32_swap_b32_e32 v178, v180
	ds_read_b128 v[214:217], v148 offset:40960
	v_permlane32_swap_b32_e32 v179, v181
	s_waitcnt lgkmcnt(5)
	v_mfma_f32_32x32x16_bf16 v[64:79], v[194:197], v[124:127], 0
	v_exp_f32_e32 v104, v104
	v_exp_f32_e32 v105, v105
	ds_read_b128 v[218:221], v143 offset:40960
	s_waitcnt lgkmcnt(5)
	v_mfma_f32_32x32x16_bf16 v[64:79], v[198:201], v[120:123], v[64:79]
	v_exp_f32_e32 v106, v106
	v_exp_f32_e32 v107, v107
	v_add_f32_e32 v234, v234, v104
	ds_read_b128 v[222:225], v141 offset:40960
	ds_read_b64_tr_b16 v[226:227], v151 offset:0
	ds_read_b64_tr_b16 v[228:229], v151 offset:2048
	s_waitcnt lgkmcnt(7)
	v_mfma_f32_32x32x16_bf16 v[64:79], v[202:205], v[116:119], v[64:79]
	v_exp_f32_e32 v108, v108
	v_exp_f32_e32 v109, v109
	v_add_f32_e32 v235, v235, v105
	v_add_f32_e32 v234, v234, v106
	ds_read_b64_tr_b16 v[230:231], v151 offset:512
	ds_read_b64_tr_b16 v[232:233], v151 offset:2560
	s_waitcnt lgkmcnt(8)
	v_mfma_f32_32x32x16_bf16 v[64:79], v[206:209], v[112:115], v[64:79]
	v_exp_f32_e32 v110, v110
	v_exp_f32_e32 v111, v111
	v_add_f32_e32 v235, v235, v107
	v_add_f32_e32 v234, v234, v108
	ds_read_b64_tr_b16 v[238:239], v151 offset:1024
	ds_read_b64_tr_b16 v[240:241], v151 offset:3072
	s_waitcnt lgkmcnt(9)
	v_mfma_f32_32x32x16_bf16 v[80:95], v[210:213], v[124:127], 0
	v_add_f32_e32 v235, v235, v109
	v_add_f32_e32 v234, v234, v110
	v_add_f32_e32 v235, v235, v111
	v_cvt_pk_bf16_f32 v182, v104, v105
	v_cvt_pk_bf16_f32 v184, v108, v109
	ds_read_b64_tr_b16 v[242:243], v151 offset:1536
	ds_read_b64_tr_b16 v[244:245], v151 offset:3584
	s_waitcnt lgkmcnt(10)
	v_mfma_f32_32x32x16_bf16 v[80:95], v[214:217], v[120:123], v[80:95]
	v_cvt_pk_bf16_f32 v183, v106, v107
	v_cvt_pk_bf16_f32 v185, v110, v111
	v_permlane32_swap_b32_e32 v182, v184
	ds_read_b64_tr_b16 v[246:247], v151 offset:4096
	ds_read_b64_tr_b16 v[248:249], v151 offset:6144
	v_permlane32_swap_b32_e32 v183, v185
	s_waitcnt lgkmcnt(11)
	v_mfma_f32_32x32x16_bf16 v[80:95], v[218:221], v[116:119], v[80:95]
	v_exp_f32_e32 v162, v162
	v_exp_f32_e32 v163, v163
	ds_read_b64_tr_b16 v[250:251], v151 offset:4608
	ds_read_b64_tr_b16 v[252:253], v151 offset:6656
	s_waitcnt lgkmcnt(12)
	v_mfma_f32_32x32x16_bf16 v[80:95], v[222:225], v[112:115], v[80:95]
	v_exp_f32_e32 v164, v164
	v_exp_f32_e32 v165, v165
	v_add_f32_e32 v234, v234, v162
	ds_read_b64_tr_b16 v[152:153], v151 offset:5120
	ds_read_b64_tr_b16 v[154:155], v151 offset:7168
	s_waitcnt lgkmcnt(12)
	v_mfma_f32_32x32x16_bf16 v[48:63], v[178:181], v[226:229], v[48:63]
	v_exp_f32_e32 v166, v166
	v_exp_f32_e32 v167, v167
	v_add_f32_e32 v235, v235, v163
	v_add_f32_e32 v234, v234, v164
	ds_read_b64_tr_b16 v[226:227], v151 offset:5632
	ds_read_b64_tr_b16 v[228:229], v151 offset:7680
	s_waitcnt lgkmcnt(12)
	v_mfma_f32_32x32x16_bf16 v[32:47], v[178:181], v[230:233], v[32:47]
	v_exp_f32_e32 v168, v168
	v_exp_f32_e32 v169, v169
	v_add_f32_e32 v235, v235, v165
	v_add_f32_e32 v234, v234, v166
	ds_read_b64_tr_b16 v[230:231], v151 offset:8192
	ds_read_b64_tr_b16 v[232:233], v151 offset:10240
	s_waitcnt lgkmcnt(12)
	v_mfma_f32_32x32x16_bf16 v[16:31], v[178:181], v[238:241], v[16:31]
	v_add_f32_e32 v235, v235, v167
	v_add_f32_e32 v234, v234, v168
	v_add_f32_e32 v235, v235, v169
	v_cvt_pk_bf16_f32 v186, v162, v163
	v_cvt_pk_bf16_f32 v188, v166, v167
	ds_read_b64_tr_b16 v[238:239], v151 offset:8704
	ds_read_b64_tr_b16 v[240:241], v151 offset:10752
	s_waitcnt lgkmcnt(12)
	v_mfma_f32_32x32x16_bf16 v[0:15], v[178:181], v[242:245], v[0:15]
	v_cvt_pk_bf16_f32 v187, v164, v165
	v_cvt_pk_bf16_f32 v189, v168, v169
	v_permlane32_swap_b32_e32 v186, v188
	ds_read_b64_tr_b16 v[242:243], v151 offset:9216
	ds_read_b64_tr_b16 v[244:245], v151 offset:11264
	v_permlane32_swap_b32_e32 v187, v189
	s_waitcnt lgkmcnt(12)
	v_mfma_f32_32x32x16_bf16 v[48:63], v[182:185], v[246:249], v[48:63]
	v_exp_f32_e32 v170, v170
	v_exp_f32_e32 v171, v171
	ds_read_b64_tr_b16 v[246:247], v151 offset:9728
	ds_read_b64_tr_b16 v[248:249], v151 offset:11776
	s_waitcnt lgkmcnt(12)
	v_mfma_f32_32x32x16_bf16 v[32:47], v[182:185], v[250:253], v[32:47]
	v_exp_f32_e32 v172, v172
	v_exp_f32_e32 v173, v173
	v_add_f32_e32 v234, v234, v170
	ds_read_b64_tr_b16 v[250:251], v151 offset:12288
	ds_read_b64_tr_b16 v[252:253], v151 offset:14336
	s_waitcnt lgkmcnt(12)
	v_mfma_f32_32x32x16_bf16 v[16:31], v[182:185], v[152:155], v[16:31]
	v_exp_f32_e32 v174, v174
	v_exp_f32_e32 v175, v175
	v_add_f32_e32 v235, v235, v171
	v_add_f32_e32 v234, v234, v172
	ds_read_b64_tr_b16 v[152:153], v151 offset:12800
	ds_read_b64_tr_b16 v[154:155], v151 offset:14848
	s_waitcnt lgkmcnt(12)
	v_mfma_f32_32x32x16_bf16 v[0:15], v[182:185], v[226:229], v[0:15]
	v_exp_f32_e32 v176, v176
	v_exp_f32_e32 v177, v177
	v_add_f32_e32 v235, v235, v173
	v_add_f32_e32 v234, v234, v174
	ds_read_b64_tr_b16 v[226:227], v151 offset:13312
	ds_read_b64_tr_b16 v[228:229], v151 offset:15360
	s_waitcnt lgkmcnt(12)
	v_mfma_f32_32x32x16_bf16 v[48:63], v[186:189], v[230:233], v[48:63]
	v_add_f32_e32 v235, v235, v175
	v_add_f32_e32 v234, v234, v176
	v_add_f32_e32 v235, v235, v177
	v_cvt_pk_bf16_f32 v190, v170, v171
	v_cvt_pk_bf16_f32 v192, v174, v175
	ds_read_b64_tr_b16 v[230:231], v151 offset:13824
	ds_read_b64_tr_b16 v[232:233], v151 offset:15872
	s_waitcnt lgkmcnt(12)
	v_mfma_f32_32x32x16_bf16 v[32:47], v[186:189], v[238:241], v[32:47]
	s_add_i32 s62, s62, 0x4000
	s_cmp_ge_u32 s62, 0x14000
	s_cselect_b32 s69, 0x14000, 0
	s_sub_i32 s62, s62, s69
	v_add_u32_e32 v151, s62, v140
	v_cvt_pk_bf16_f32 v191, v172, v173
	v_cvt_pk_bf16_f32 v193, v176, v177
	v_permlane32_swap_b32_e32 v190, v192
	s_nop 0
	v_permlane32_swap_b32_e32 v191, v193
	s_waitcnt lgkmcnt(10)
	v_mfma_f32_32x32x16_bf16 v[16:31], v[186:189], v[242:245], v[16:31]
	v_exp_f32_e32 v64, v64
	v_exp_f32_e32 v65, v65
	ds_read_b128 v[194:197], v149 offset:49152
	s_waitcnt lgkmcnt(9)
	v_mfma_f32_32x32x16_bf16 v[0:15], v[186:189], v[246:249], v[0:15]
	v_exp_f32_e32 v66, v66
	v_exp_f32_e32 v67, v67
	v_add_f32_e32 v234, v234, v64
	ds_read_b128 v[198:201], v148 offset:49152
	s_waitcnt lgkmcnt(8)
	v_mfma_f32_32x32x16_bf16 v[48:63], v[190:193], v[250:253], v[48:63]
	v_exp_f32_e32 v68, v68
	v_exp_f32_e32 v69, v69
	v_add_f32_e32 v235, v235, v65
	v_add_f32_e32 v234, v234, v66
	ds_read_b128 v[202:205], v143 offset:49152
	s_waitcnt lgkmcnt(7)
	v_mfma_f32_32x32x16_bf16 v[32:47], v[190:193], v[152:155], v[32:47]
	v_exp_f32_e32 v70, v70
	v_exp_f32_e32 v71, v71
	v_add_f32_e32 v235, v235, v67
	v_add_f32_e32 v234, v234, v68
	ds_read_b128 v[206:209], v141 offset:49152
	s_waitcnt lgkmcnt(6)
	v_mfma_f32_32x32x16_bf16 v[16:31], v[190:193], v[226:229], v[16:31]
	v_add_f32_e32 v235, v235, v69
	v_add_f32_e32 v234, v234, v70
	v_add_f32_e32 v235, v235, v71
	v_cvt_pk_bf16_f32 v178, v64, v65
	v_cvt_pk_bf16_f32 v180, v68, v69
	ds_read_b128 v[210:213], v149 offset:57344
	s_waitcnt lgkmcnt(5)
	v_mfma_f32_32x32x16_bf16 v[0:15], v[190:193], v[230:233], v[0:15]
	v_cvt_pk_bf16_f32 v179, v66, v67
	v_cvt_pk_bf16_f32 v181, v70, v71
	v_permlane32_swap_b32_e32 v178, v180
	ds_read_b128 v[214:217], v148 offset:57344
	v_permlane32_swap_b32_e32 v179, v181
	s_waitcnt lgkmcnt(5)
	v_mfma_f32_32x32x16_bf16 v[96:111], v[194:197], v[124:127], 0
	v_exp_f32_e32 v72, v72
	v_exp_f32_e32 v73, v73
	ds_read_b128 v[218:221], v143 offset:57344
	s_waitcnt lgkmcnt(5)
	v_mfma_f32_32x32x16_bf16 v[96:111], v[198:201], v[120:123], v[96:111]
	v_exp_f32_e32 v74, v74
	v_exp_f32_e32 v75, v75
	v_add_f32_e32 v234, v234, v72
	ds_read_b128 v[222:225], v141 offset:57344
	ds_read_b64_tr_b16 v[226:227], v151 offset:0
	ds_read_b64_tr_b16 v[228:229], v151 offset:2048
	s_waitcnt lgkmcnt(7)
	v_mfma_f32_32x32x16_bf16 v[96:111], v[202:205], v[116:119], v[96:111]
	v_exp_f32_e32 v76, v76
	v_exp_f32_e32 v77, v77
	v_add_f32_e32 v235, v235, v73
	v_add_f32_e32 v234, v234, v74
	ds_read_b64_tr_b16 v[230:231], v151 offset:512
	ds_read_b64_tr_b16 v[232:233], v151 offset:2560
	s_waitcnt lgkmcnt(8)
	v_mfma_f32_32x32x16_bf16 v[96:111], v[206:209], v[112:115], v[96:111]
	v_exp_f32_e32 v78, v78
	v_exp_f32_e32 v79, v79
	v_add_f32_e32 v235, v235, v75
	v_add_f32_e32 v234, v234, v76
	ds_read_b64_tr_b16 v[238:239], v151 offset:1024
	ds_read_b64_tr_b16 v[240:241], v151 offset:3072
	s_waitcnt lgkmcnt(9)
	v_mfma_f32_32x32x16_bf16 v[162:177], v[210:213], v[124:127], 0
	v_add_f32_e32 v235, v235, v77
	v_add_f32_e32 v234, v234, v78
	v_add_f32_e32 v235, v235, v79
	v_cvt_pk_bf16_f32 v182, v72, v73
	v_cvt_pk_bf16_f32 v184, v76, v77
	ds_read_b64_tr_b16 v[242:243], v151 offset:1536
	ds_read_b64_tr_b16 v[244:245], v151 offset:3584
	s_waitcnt lgkmcnt(10)
	v_mfma_f32_32x32x16_bf16 v[162:177], v[214:217], v[120:123], v[162:177]
	v_cvt_pk_bf16_f32 v183, v74, v75
	v_cvt_pk_bf16_f32 v185, v78, v79
	v_permlane32_swap_b32_e32 v182, v184
	ds_read_b64_tr_b16 v[246:247], v151 offset:4096
	ds_read_b64_tr_b16 v[248:249], v151 offset:6144
	v_permlane32_swap_b32_e32 v183, v185
	s_waitcnt lgkmcnt(11)
	v_mfma_f32_32x32x16_bf16 v[162:177], v[218:221], v[116:119], v[162:177]
	v_exp_f32_e32 v80, v80
	v_exp_f32_e32 v81, v81
	ds_read_b64_tr_b16 v[250:251], v151 offset:4608
	ds_read_b64_tr_b16 v[252:253], v151 offset:6656
	s_waitcnt lgkmcnt(12)
	v_mfma_f32_32x32x16_bf16 v[162:177], v[222:225], v[112:115], v[162:177]
	v_exp_f32_e32 v82, v82
	v_exp_f32_e32 v83, v83
	v_add_f32_e32 v234, v234, v80
	ds_read_b64_tr_b16 v[152:153], v151 offset:5120
	ds_read_b64_tr_b16 v[154:155], v151 offset:7168
	s_waitcnt lgkmcnt(12)
	v_mfma_f32_32x32x16_bf16 v[48:63], v[178:181], v[226:229], v[48:63]
	v_exp_f32_e32 v84, v84
	v_exp_f32_e32 v85, v85
	v_add_f32_e32 v235, v235, v81
	v_add_f32_e32 v234, v234, v82
	ds_read_b64_tr_b16 v[226:227], v151 offset:5632
	ds_read_b64_tr_b16 v[228:229], v151 offset:7680
	s_waitcnt lgkmcnt(12)
	v_mfma_f32_32x32x16_bf16 v[32:47], v[178:181], v[230:233], v[32:47]
	v_exp_f32_e32 v86, v86
	v_exp_f32_e32 v87, v87
	v_add_f32_e32 v235, v235, v83
	v_add_f32_e32 v234, v234, v84
	ds_read_b64_tr_b16 v[230:231], v151 offset:8192
	ds_read_b64_tr_b16 v[232:233], v151 offset:10240
	s_waitcnt lgkmcnt(12)
	v_mfma_f32_32x32x16_bf16 v[16:31], v[178:181], v[238:241], v[16:31]
	v_add_f32_e32 v235, v235, v85
	v_add_f32_e32 v234, v234, v86
	v_add_f32_e32 v235, v235, v87
	v_cvt_pk_bf16_f32 v186, v80, v81
	v_cvt_pk_bf16_f32 v188, v84, v85
	ds_read_b64_tr_b16 v[238:239], v151 offset:8704
	ds_read_b64_tr_b16 v[240:241], v151 offset:10752
	s_waitcnt lgkmcnt(12)
	v_mfma_f32_32x32x16_bf16 v[0:15], v[178:181], v[242:245], v[0:15]
	v_cvt_pk_bf16_f32 v187, v82, v83
	v_cvt_pk_bf16_f32 v189, v86, v87
	v_permlane32_swap_b32_e32 v186, v188
	ds_read_b64_tr_b16 v[242:243], v151 offset:9216
	ds_read_b64_tr_b16 v[244:245], v151 offset:11264
	v_permlane32_swap_b32_e32 v187, v189
	s_waitcnt lgkmcnt(12)
	v_mfma_f32_32x32x16_bf16 v[48:63], v[182:185], v[246:249], v[48:63]
	v_exp_f32_e32 v88, v88
	v_exp_f32_e32 v89, v89
	ds_read_b64_tr_b16 v[246:247], v151 offset:9728
	ds_read_b64_tr_b16 v[248:249], v151 offset:11776
	s_waitcnt lgkmcnt(12)
	v_mfma_f32_32x32x16_bf16 v[32:47], v[182:185], v[250:253], v[32:47]
	v_exp_f32_e32 v90, v90
	v_exp_f32_e32 v91, v91
	v_add_f32_e32 v234, v234, v88
	ds_read_b64_tr_b16 v[250:251], v151 offset:12288
	ds_read_b64_tr_b16 v[252:253], v151 offset:14336
	s_waitcnt lgkmcnt(12)
	v_mfma_f32_32x32x16_bf16 v[16:31], v[182:185], v[152:155], v[16:31]
	v_exp_f32_e32 v92, v92
	v_exp_f32_e32 v93, v93
	v_add_f32_e32 v235, v235, v89
	v_add_f32_e32 v234, v234, v90
	ds_read_b64_tr_b16 v[152:153], v151 offset:12800
	ds_read_b64_tr_b16 v[154:155], v151 offset:14848
	s_waitcnt lgkmcnt(12)
	v_mfma_f32_32x32x16_bf16 v[0:15], v[182:185], v[226:229], v[0:15]
	v_exp_f32_e32 v94, v94
	v_exp_f32_e32 v95, v95
	v_add_f32_e32 v235, v235, v91
	v_add_f32_e32 v234, v234, v92
	ds_read_b64_tr_b16 v[226:227], v151 offset:13312
	ds_read_b64_tr_b16 v[228:229], v151 offset:15360
	s_waitcnt lgkmcnt(12)
	v_mfma_f32_32x32x16_bf16 v[48:63], v[186:189], v[230:233], v[48:63]
	v_add_f32_e32 v235, v235, v93
	v_add_f32_e32 v234, v234, v94
	v_add_f32_e32 v235, v235, v95
	v_cvt_pk_bf16_f32 v190, v88, v89
	v_cvt_pk_bf16_f32 v192, v92, v93
	ds_read_b64_tr_b16 v[230:231], v151 offset:13824
	ds_read_b64_tr_b16 v[232:233], v151 offset:15872
	s_waitcnt lgkmcnt(12)
	v_mfma_f32_32x32x16_bf16 v[32:47], v[186:189], v[238:241], v[32:47]
	s_waitcnt vmcnt(0)
	s_barrier
	s_add_i32 s62, s62, 0x4000
	s_cmp_ge_u32 s62, 0x14000
	s_cselect_b32 s69, 0x14000, 0
	s_sub_i32 s62, s62, s69
	v_add_u32_e32 v151, s62, v140
	v_cvt_pk_bf16_f32 v191, v90, v91
	v_cvt_pk_bf16_f32 v193, v94, v95
	v_permlane32_swap_b32_e32 v190, v192
	s_nop 0
	v_permlane32_swap_b32_e32 v191, v193
	s_waitcnt lgkmcnt(10)
	v_mfma_f32_32x32x16_bf16 v[16:31], v[186:189], v[242:245], v[16:31]
	v_exp_f32_e32 v96, v96
	v_exp_f32_e32 v97, v97
	s_waitcnt lgkmcnt(8)
	v_mfma_f32_32x32x16_bf16 v[0:15], v[186:189], v[246:249], v[0:15]
	v_exp_f32_e32 v98, v98
	v_exp_f32_e32 v99, v99
	v_add_f32_e32 v234, v234, v96
	s_waitcnt lgkmcnt(6)
	v_mfma_f32_32x32x16_bf16 v[48:63], v[190:193], v[250:253], v[48:63]
	v_exp_f32_e32 v100, v100
	v_exp_f32_e32 v101, v101
	v_add_f32_e32 v235, v235, v97
	v_add_f32_e32 v234, v234, v98
	s_waitcnt lgkmcnt(4)
	v_mfma_f32_32x32x16_bf16 v[32:47], v[190:193], v[152:155], v[32:47]
	v_exp_f32_e32 v102, v102
	v_exp_f32_e32 v103, v103
	v_add_f32_e32 v235, v235, v99
	v_add_f32_e32 v234, v234, v100
	s_waitcnt lgkmcnt(2)
	v_mfma_f32_32x32x16_bf16 v[16:31], v[190:193], v[226:229], v[16:31]
	v_add_f32_e32 v235, v235, v101
	v_add_f32_e32 v234, v234, v102
	v_add_f32_e32 v235, v235, v103
	v_cvt_pk_bf16_f32 v178, v96, v97
	v_cvt_pk_bf16_f32 v180, v100, v101
	s_waitcnt lgkmcnt(0)
	v_mfma_f32_32x32x16_bf16 v[0:15], v[190:193], v[230:233], v[0:15]
	v_cvt_pk_bf16_f32 v179, v98, v99
	v_cvt_pk_bf16_f32 v181, v102, v103
	v_permlane32_swap_b32_e32 v178, v180
	s_nop 0
	v_permlane32_swap_b32_e32 v179, v181
	v_exp_f32_e32 v104, v104
	v_exp_f32_e32 v105, v105
	v_exp_f32_e32 v106, v106
	v_exp_f32_e32 v107, v107
	v_add_f32_e32 v234, v234, v104
	ds_read_b64_tr_b16 v[226:227], v151 offset:0
	ds_read_b64_tr_b16 v[228:229], v151 offset:2048
	v_exp_f32_e32 v108, v108
	v_exp_f32_e32 v109, v109
	v_add_f32_e32 v235, v235, v105
	v_add_f32_e32 v234, v234, v106
	ds_read_b64_tr_b16 v[230:231], v151 offset:512
	ds_read_b64_tr_b16 v[232:233], v151 offset:2560
	v_exp_f32_e32 v110, v110
	v_exp_f32_e32 v111, v111
	v_add_f32_e32 v235, v235, v107
	v_add_f32_e32 v234, v234, v108
	ds_read_b64_tr_b16 v[238:239], v151 offset:1024
	ds_read_b64_tr_b16 v[240:241], v151 offset:3072
	v_add_f32_e32 v235, v235, v109
	v_add_f32_e32 v234, v234, v110
	v_add_f32_e32 v235, v235, v111
	v_cvt_pk_bf16_f32 v182, v104, v105
	v_cvt_pk_bf16_f32 v184, v108, v109
	ds_read_b64_tr_b16 v[242:243], v151 offset:1536
	ds_read_b64_tr_b16 v[244:245], v151 offset:3584
	v_cvt_pk_bf16_f32 v183, v106, v107
	v_cvt_pk_bf16_f32 v185, v110, v111
	v_permlane32_swap_b32_e32 v182, v184
	ds_read_b64_tr_b16 v[246:247], v151 offset:4096
	ds_read_b64_tr_b16 v[248:249], v151 offset:6144
	v_permlane32_swap_b32_e32 v183, v185
	v_exp_f32_e32 v162, v162
	v_exp_f32_e32 v163, v163
	ds_read_b64_tr_b16 v[250:251], v151 offset:4608
	ds_read_b64_tr_b16 v[252:253], v151 offset:6656
	v_exp_f32_e32 v164, v164
	v_exp_f32_e32 v165, v165
	v_add_f32_e32 v234, v234, v162
	ds_read_b64_tr_b16 v[152:153], v151 offset:5120
	ds_read_b64_tr_b16 v[154:155], v151 offset:7168
	s_waitcnt lgkmcnt(12)
	v_mfma_f32_32x32x16_bf16 v[48:63], v[178:181], v[226:229], v[48:63]
	v_exp_f32_e32 v166, v166
	v_exp_f32_e32 v167, v167
	v_add_f32_e32 v235, v235, v163
	v_add_f32_e32 v234, v234, v164
	ds_read_b64_tr_b16 v[226:227], v151 offset:5632
	ds_read_b64_tr_b16 v[228:229], v151 offset:7680
	s_waitcnt lgkmcnt(12)
	v_mfma_f32_32x32x16_bf16 v[32:47], v[178:181], v[230:233], v[32:47]
	v_exp_f32_e32 v168, v168
	v_exp_f32_e32 v169, v169
	v_add_f32_e32 v235, v235, v165
	v_add_f32_e32 v234, v234, v166
	ds_read_b64_tr_b16 v[230:231], v151 offset:8192
	ds_read_b64_tr_b16 v[232:233], v151 offset:10240
	s_waitcnt lgkmcnt(12)
	v_mfma_f32_32x32x16_bf16 v[16:31], v[178:181], v[238:241], v[16:31]
	v_add_f32_e32 v235, v235, v167
	v_add_f32_e32 v234, v234, v168
	v_add_f32_e32 v235, v235, v169
	v_cvt_pk_bf16_f32 v186, v162, v163
	v_cvt_pk_bf16_f32 v188, v166, v167
	ds_read_b64_tr_b16 v[238:239], v151 offset:8704
	ds_read_b64_tr_b16 v[240:241], v151 offset:10752
	s_waitcnt lgkmcnt(12)
	v_mfma_f32_32x32x16_bf16 v[0:15], v[178:181], v[242:245], v[0:15]
	v_cvt_pk_bf16_f32 v187, v164, v165
	v_cvt_pk_bf16_f32 v189, v168, v169
	v_permlane32_swap_b32_e32 v186, v188
	ds_read_b64_tr_b16 v[242:243], v151 offset:9216
	ds_read_b64_tr_b16 v[244:245], v151 offset:11264
	v_permlane32_swap_b32_e32 v187, v189
	s_waitcnt lgkmcnt(12)
	v_mfma_f32_32x32x16_bf16 v[48:63], v[182:185], v[246:249], v[48:63]
	v_exp_f32_e32 v170, v170
	v_exp_f32_e32 v171, v171
	ds_read_b64_tr_b16 v[246:247], v151 offset:9728
	ds_read_b64_tr_b16 v[248:249], v151 offset:11776
	s_waitcnt lgkmcnt(12)
	v_mfma_f32_32x32x16_bf16 v[32:47], v[182:185], v[250:253], v[32:47]
	v_exp_f32_e32 v172, v172
	v_exp_f32_e32 v173, v173
	v_add_f32_e32 v234, v234, v170
	ds_read_b64_tr_b16 v[250:251], v151 offset:12288
	ds_read_b64_tr_b16 v[252:253], v151 offset:14336
	s_waitcnt lgkmcnt(12)
	v_mfma_f32_32x32x16_bf16 v[16:31], v[182:185], v[152:155], v[16:31]
	v_exp_f32_e32 v174, v174
	v_exp_f32_e32 v175, v175
	v_add_f32_e32 v235, v235, v171
	v_add_f32_e32 v234, v234, v172
	ds_read_b64_tr_b16 v[152:153], v151 offset:12800
	ds_read_b64_tr_b16 v[154:155], v151 offset:14848
	s_waitcnt lgkmcnt(12)
	v_mfma_f32_32x32x16_bf16 v[0:15], v[182:185], v[226:229], v[0:15]
	v_exp_f32_e32 v176, v176
	v_exp_f32_e32 v177, v177
	v_add_f32_e32 v235, v235, v173
	v_add_f32_e32 v234, v234, v174
	ds_read_b64_tr_b16 v[226:227], v151 offset:13312
	ds_read_b64_tr_b16 v[228:229], v151 offset:15360
	s_waitcnt lgkmcnt(12)
	v_mfma_f32_32x32x16_bf16 v[48:63], v[186:189], v[230:233], v[48:63]
	v_add_f32_e32 v235, v235, v175
	v_add_f32_e32 v234, v234, v176
	v_add_f32_e32 v235, v235, v177
	v_cvt_pk_bf16_f32 v190, v170, v171
	v_cvt_pk_bf16_f32 v192, v174, v175
	ds_read_b64_tr_b16 v[230:231], v151 offset:13824
	ds_read_b64_tr_b16 v[232:233], v151 offset:15872
	s_waitcnt lgkmcnt(12)
	v_mfma_f32_32x32x16_bf16 v[32:47], v[186:189], v[238:241], v[32:47]
	s_add_i32 s62, s62, 0x4000
	s_cmp_ge_u32 s62, 0x14000
	s_cselect_b32 s69, 0x14000, 0
	s_sub_i32 s62, s62, s69
	v_add_u32_e32 v151, s62, v140
	v_cvt_pk_bf16_f32 v191, v172, v173
	v_cvt_pk_bf16_f32 v193, v176, v177
	v_permlane32_swap_b32_e32 v190, v192
	s_nop 0
	v_permlane32_swap_b32_e32 v191, v193
	s_waitcnt lgkmcnt(10)
	v_mfma_f32_32x32x16_bf16 v[16:31], v[186:189], v[242:245], v[16:31]
	s_waitcnt lgkmcnt(8)
	v_mfma_f32_32x32x16_bf16 v[0:15], v[186:189], v[246:249], v[0:15]
	s_waitcnt lgkmcnt(6)
	v_mfma_f32_32x32x16_bf16 v[48:63], v[190:193], v[250:253], v[48:63]
	s_waitcnt lgkmcnt(4)
	v_mfma_f32_32x32x16_bf16 v[32:47], v[190:193], v[152:155], v[32:47]
	s_waitcnt lgkmcnt(2)
	v_mfma_f32_32x32x16_bf16 v[16:31], v[190:193], v[226:229], v[16:31]
	s_waitcnt lgkmcnt(0)
	v_mfma_f32_32x32x16_bf16 v[0:15], v[190:193], v[230:233], v[0:15]
	v_add_f32_e32 v68, v234, v235
	v_mov_b32_e32 v69, 0
	v_mov_b32_e32 v71, 0
	v_mov_b32_e32 v70, v68
	v_mov_b32_e32 v128, 0
	s_nop 0
	v_permlane32_swap_b32_e32 v68, v70
	s_and_b32 s4, s35, 0x3fffffc0
	s_lshl_b32 s4, s4, 2
	s_add_i32 s7, s4, 0
	s_add_i32 s7, s7, 0x24000
	s_setprio 0
	v_add_f32_e32 v64, v68, v70
	v_lshl_add_u32 v66, v136, 2, s7
	ds_write_b32 v66, v64
	global_load_dword v116, v129, s[14:15]
	v_lshlrev_b32_e32 v117, 2, v136
	global_load_dword v112, v117, s[58:59] offset:0
	global_load_dword v113, v117, s[58:59] offset:128
	global_load_dword v114, v117, s[58:59] offset:256
	global_load_dword v115, v117, s[58:59] offset:384
	s_lshl_b32 s4, s19, 4
	s_add_i32 s4, s18, s4
	s_lshl_b32 s5, s4, 13
	s_add_u32 s42, s65, s6
	s_addc_u32 s43, s20, 0
	s_add_u32 s42, s42, s5
	s_addc_u32 s43, s43, 0
	s_lshl_b32 s5, s4, 11
	s_add_u32 s46, s21, s6
	s_addc_u32 s47, s22, 0
	s_add_u32 s46, s46, s5
	s_addc_u32 s47, s47, 0
	v_lshlrev_b32_e32 v118, 1, v136
	v_lshl_add_u32 v119, v137, 13, v118
	v_lshl_add_u32 v118, v137, 15, v118
	global_load_ushort v162, v118, s[42:43] offset:0
	global_load_ushort v163, v118, s[42:43] offset:64
	global_load_ushort v164, v118, s[42:43] offset:128
	global_load_ushort v165, v118, s[42:43] offset:192
	s_add_u32 s42, s42, 0x2000
	s_addc_u32 s43, s43, 0
	global_load_ushort v166, v118, s[42:43] offset:0
	global_load_ushort v167, v118, s[42:43] offset:64
	global_load_ushort v168, v118, s[42:43] offset:128
	global_load_ushort v169, v118, s[42:43] offset:192
	s_add_u32 s42, s42, 0x2000
	s_addc_u32 s43, s43, 0
	global_load_ushort v170, v118, s[42:43] offset:0
	global_load_ushort v171, v118, s[42:43] offset:64
	global_load_ushort v172, v118, s[42:43] offset:128
	global_load_ushort v173, v118, s[42:43] offset:192
	s_add_u32 s42, s42, 0x2000
	s_addc_u32 s43, s43, 0
	global_load_ushort v174, v118, s[42:43] offset:0
	global_load_ushort v175, v118, s[42:43] offset:64
	global_load_ushort v176, v118, s[42:43] offset:128
	global_load_ushort v177, v118, s[42:43] offset:192
	s_add_u32 s42, s42, 0xa000
	s_addc_u32 s43, s43, 0
	global_load_ushort v178, v118, s[42:43] offset:0
	global_load_ushort v179, v118, s[42:43] offset:64
	global_load_ushort v180, v118, s[42:43] offset:128
	global_load_ushort v181, v118, s[42:43] offset:192
	s_add_u32 s42, s42, 0x2000
	s_addc_u32 s43, s43, 0
	global_load_ushort v182, v118, s[42:43] offset:0
	global_load_ushort v183, v118, s[42:43] offset:64
	global_load_ushort v184, v118, s[42:43] offset:128
	global_load_ushort v185, v118, s[42:43] offset:192
	s_add_u32 s42, s42, 0x2000
	s_addc_u32 s43, s43, 0
	global_load_ushort v186, v118, s[42:43] offset:0
	global_load_ushort v187, v118, s[42:43] offset:64
	global_load_ushort v188, v118, s[42:43] offset:128
	global_load_ushort v189, v118, s[42:43] offset:192
	s_add_u32 s42, s42, 0x2000
	s_addc_u32 s43, s43, 0
	global_load_ushort v190, v118, s[42:43] offset:0
	global_load_ushort v191, v118, s[42:43] offset:64
	global_load_ushort v192, v118, s[42:43] offset:128
	global_load_ushort v193, v118, s[42:43] offset:192
	v_add_u32_e32 v65, s7, v130
	s_waitcnt lgkmcnt(0)
	ds_read_b128 v[80:83], v65
	ds_read_b128 v[84:87], v65 offset:32
	ds_read_b128 v[88:91], v65 offset:64
	ds_read_b128 v[92:95], v65 offset:96
	s_waitcnt lgkmcnt(0)
	v_rcp_f32_e32 v96, v80
	v_rcp_f32_e32 v97, v81
	v_rcp_f32_e32 v98, v82
	v_rcp_f32_e32 v99, v83
	v_rcp_f32_e32 v100, v84
	v_rcp_f32_e32 v101, v85
	v_rcp_f32_e32 v102, v86
	v_rcp_f32_e32 v103, v87
	v_rcp_f32_e32 v104, v88
	v_rcp_f32_e32 v105, v89
	v_rcp_f32_e32 v106, v90
	v_rcp_f32_e32 v107, v91
	v_rcp_f32_e32 v108, v92
	v_rcp_f32_e32 v109, v93
	v_rcp_f32_e32 v110, v94
	v_rcp_f32_e32 v111, v95
	s_waitcnt vmcnt(36)
	v_readfirstlane_b32 s5, v116
	s_nop 3
	s_cmp_eq_u32 s19, 0
	s_cselect_b32 s5, 1.0, s5
	s_cselect_b32 s10, 1.0, -1.0
	s_cselect_b32 s40, 0, 0x2000
	s_cselect_b32 s41, 0x2000, 0
	v_mul_f32_e32 v96, s5, v96
	v_mul_f32_e32 v97, s5, v97
	v_mul_f32_e32 v98, s5, v98
	v_mul_f32_e32 v99, s5, v99
	v_mul_f32_e32 v100, s5, v100
	v_mul_f32_e32 v101, s5, v101
	v_mul_f32_e32 v102, s5, v102
	v_mul_f32_e32 v103, s5, v103
	v_mul_f32_e32 v104, s5, v104
	v_mul_f32_e32 v105, s5, v105
	v_mul_f32_e32 v106, s5, v106
	v_mul_f32_e32 v107, s5, v107
	v_mul_f32_e32 v108, s5, v108
	v_mul_f32_e32 v109, s5, v109
	v_mul_f32_e32 v110, s5, v110
	v_mul_f32_e32 v111, s5, v111
	s_waitcnt vmcnt(32)
	v_mov_b32_e32 v120, 0x3f4ccccd
	v_mul_f32_e32 v120, s10, v120
	v_mul_f32_e32 v112, v120, v112
	v_mul_f32_e32 v113, v120, v113
	v_mul_f32_e32 v114, v120, v114
	v_mul_f32_e32 v115, v120, v115
	s_barrier
	s_lshl_b32 s11, s34, 14
	v_lshl_add_u32 v121, v137, 11, v117
	v_add_u32_e32 v121, s11, v121
	s_add_i32 s62, s40, 0x0
	v_add_u32_e32 v140, s62, v121
	s_add_i32 s62, s41, 0x0
	v_add_u32_e32 v122, s62, v121
	s_add_i32 s62, s40, 0x400
	v_add_u32_e32 v141, s62, v121
	s_add_i32 s62, s41, 0x400
	v_add_u32_e32 v123, s62, v121
	s_add_i32 s62, s40, 0x1000
	v_add_u32_e32 v142, s62, v121
	s_add_i32 s62, s41, 0x1000
	v_add_u32_e32 v124, s62, v121
	s_add_i32 s62, s40, 0x1400
	v_add_u32_e32 v143, s62, v121
	s_add_i32 s62, s41, 0x1400
	v_add_u32_e32 v125, s62, v121
	s_cmp_eq_u32 s19, 0
	s_cbranch_scc0 .Lde_c1
	v_mul_f32_e32 v194, v48, v96
	v_mul_f32_e32 v202, v32, v96
	v_mul_f32_e32 v210, v16, v96
	v_mul_f32_e32 v218, v0, v96
	v_mul_f32_e32 v195, v49, v97
	v_mul_f32_e32 v203, v33, v97
	v_mul_f32_e32 v211, v17, v97
	v_mul_f32_e32 v219, v1, v97
	v_mul_f32_e32 v196, v50, v98
	v_mul_f32_e32 v204, v34, v98
	v_mul_f32_e32 v212, v18, v98
	v_mul_f32_e32 v220, v2, v98
	v_mul_f32_e32 v197, v51, v99
	v_mul_f32_e32 v205, v35, v99
	v_mul_f32_e32 v213, v19, v99
	v_mul_f32_e32 v221, v3, v99
	v_mul_f32_e32 v198, v52, v100
	v_mul_f32_e32 v206, v36, v100
	v_mul_f32_e32 v214, v20, v100
	v_mul_f32_e32 v222, v4, v100
	v_mul_f32_e32 v199, v53, v101
	v_mul_f32_e32 v207, v37, v101
	v_mul_f32_e32 v215, v21, v101
	v_mul_f32_e32 v223, v5, v101
	v_mul_f32_e32 v200, v54, v102
	v_mul_f32_e32 v208, v38, v102
	v_mul_f32_e32 v216, v22, v102
	v_mul_f32_e32 v224, v6, v102
	v_mul_f32_e32 v201, v55, v103
	v_mul_f32_e32 v209, v39, v103
	v_mul_f32_e32 v217, v23, v103
	v_mul_f32_e32 v225, v7, v103
	v_mul_f32_e32 v226, v56, v104
	v_mul_f32_e32 v227, v40, v104
	ds_write2_b32 v122, v226, v227 offset0:0 offset1:32
	v_mul_f32_e32 v228, v24, v104
	v_mul_f32_e32 v229, v8, v104
	ds_write2_b32 v122, v228, v229 offset0:64 offset1:96
	v_mul_f32_e32 v230, v57, v105
	v_mul_f32_e32 v231, v41, v105
	ds_write2_b32 v122, v230, v231 offset0:128 offset1:160
	v_mul_f32_e32 v232, v25, v105
	v_mul_f32_e32 v233, v9, v105
	ds_write2_b32 v122, v232, v233 offset0:192 offset1:224
	v_mul_f32_e32 v238, v58, v106
	v_mul_f32_e32 v239, v42, v106
	ds_write2_b32 v123, v238, v239 offset0:0 offset1:32
	v_mul_f32_e32 v240, v26, v106
	v_mul_f32_e32 v241, v10, v106
	ds_write2_b32 v123, v240, v241 offset0:64 offset1:96
	v_mul_f32_e32 v242, v59, v107
	v_mul_f32_e32 v243, v43, v107
	ds_write2_b32 v123, v242, v243 offset0:128 offset1:160
	v_mul_f32_e32 v244, v27, v107
	v_mul_f32_e32 v245, v11, v107
	ds_write2_b32 v123, v244, v245 offset0:192 offset1:224
	v_mul_f32_e32 v246, v60, v108
	v_mul_f32_e32 v247, v44, v108
	ds_write2_b32 v124, v246, v247 offset0:0 offset1:32
	v_mul_f32_e32 v248, v28, v108
	v_mul_f32_e32 v249, v12, v108
	ds_write2_b32 v124, v248, v249 offset0:64 offset1:96
	v_mul_f32_e32 v250, v61, v109
	v_mul_f32_e32 v251, v45, v109
	ds_write2_b32 v124, v250, v251 offset0:128 offset1:160
	v_mul_f32_e32 v252, v29, v109
	v_mul_f32_e32 v253, v13, v109
	ds_write2_b32 v124, v252, v253 offset0:192 offset1:224
	v_mul_f32_e32 v254, v62, v110
	v_mul_f32_e32 v255, v46, v110
	ds_write2_b32 v125, v254, v255 offset0:0 offset1:32
	v_mul_f32_e32 v146, v30, v110
	v_mul_f32_e32 v147, v14, v110
	ds_write2_b32 v125, v146, v147 offset0:64 offset1:96
	v_mul_f32_e32 v148, v63, v111
	v_mul_f32_e32 v149, v47, v111
	ds_write2_b32 v125, v148, v149 offset0:128 offset1:160
	v_mul_f32_e32 v150, v31, v111
	v_mul_f32_e32 v151, v15, v111
	ds_write2_b32 v125, v150, v151 offset0:192 offset1:224
	s_branch .Lde_join
.Lde_c1:
	v_mul_f32_e32 v194, v56, v104
	v_mul_f32_e32 v202, v40, v104
	v_mul_f32_e32 v210, v24, v104
	v_mul_f32_e32 v218, v8, v104
	v_mul_f32_e32 v195, v57, v105
	v_mul_f32_e32 v203, v41, v105
	v_mul_f32_e32 v211, v25, v105
	v_mul_f32_e32 v219, v9, v105
	v_mul_f32_e32 v196, v58, v106
	v_mul_f32_e32 v204, v42, v106
	v_mul_f32_e32 v212, v26, v106
	v_mul_f32_e32 v220, v10, v106
	v_mul_f32_e32 v197, v59, v107
	v_mul_f32_e32 v205, v43, v107
	v_mul_f32_e32 v213, v27, v107
	v_mul_f32_e32 v221, v11, v107
	v_mul_f32_e32 v198, v60, v108
	v_mul_f32_e32 v206, v44, v108
	v_mul_f32_e32 v214, v28, v108
	v_mul_f32_e32 v222, v12, v108
	v_mul_f32_e32 v199, v61, v109
	v_mul_f32_e32 v207, v45, v109
	v_mul_f32_e32 v215, v29, v109
	v_mul_f32_e32 v223, v13, v109
	v_mul_f32_e32 v200, v62, v110
	v_mul_f32_e32 v208, v46, v110
	v_mul_f32_e32 v216, v30, v110
	v_mul_f32_e32 v224, v14, v110
	v_mul_f32_e32 v201, v63, v111
	v_mul_f32_e32 v209, v47, v111
	v_mul_f32_e32 v217, v31, v111
	v_mul_f32_e32 v225, v15, v111
	v_mul_f32_e32 v226, v48, v96
	v_mul_f32_e32 v227, v32, v96
	ds_write2_b32 v122, v226, v227 offset0:0 offset1:32
	v_mul_f32_e32 v228, v16, v96
	v_mul_f32_e32 v229, v0, v96
	ds_write2_b32 v122, v228, v229 offset0:64 offset1:96
	v_mul_f32_e32 v230, v49, v97
	v_mul_f32_e32 v231, v33, v97
	ds_write2_b32 v122, v230, v231 offset0:128 offset1:160
	v_mul_f32_e32 v232, v17, v97
	v_mul_f32_e32 v233, v1, v97
	ds_write2_b32 v122, v232, v233 offset0:192 offset1:224
	v_mul_f32_e32 v238, v50, v98
	v_mul_f32_e32 v239, v34, v98
	ds_write2_b32 v123, v238, v239 offset0:0 offset1:32
	v_mul_f32_e32 v240, v18, v98
	v_mul_f32_e32 v241, v2, v98
	ds_write2_b32 v123, v240, v241 offset0:64 offset1:96
	v_mul_f32_e32 v242, v51, v99
	v_mul_f32_e32 v243, v35, v99
	ds_write2_b32 v123, v242, v243 offset0:128 offset1:160
	v_mul_f32_e32 v244, v19, v99
	v_mul_f32_e32 v245, v3, v99
	ds_write2_b32 v123, v244, v245 offset0:192 offset1:224
	v_mul_f32_e32 v246, v52, v100
	v_mul_f32_e32 v247, v36, v100
	ds_write2_b32 v124, v246, v247 offset0:0 offset1:32
	v_mul_f32_e32 v248, v20, v100
	v_mul_f32_e32 v249, v4, v100
	ds_write2_b32 v124, v248, v249 offset0:64 offset1:96
	v_mul_f32_e32 v250, v53, v101
	v_mul_f32_e32 v251, v37, v101
	ds_write2_b32 v124, v250, v251 offset0:128 offset1:160
	v_mul_f32_e32 v252, v21, v101
	v_mul_f32_e32 v253, v5, v101
	ds_write2_b32 v124, v252, v253 offset0:192 offset1:224
	v_mul_f32_e32 v254, v54, v102
	v_mul_f32_e32 v255, v38, v102
	ds_write2_b32 v125, v254, v255 offset0:0 offset1:32
	v_mul_f32_e32 v146, v22, v102
	v_mul_f32_e32 v147, v6, v102
	ds_write2_b32 v125, v146, v147 offset0:64 offset1:96
	v_mul_f32_e32 v148, v55, v103
	v_mul_f32_e32 v149, v39, v103
	ds_write2_b32 v125, v148, v149 offset0:128 offset1:160
	v_mul_f32_e32 v150, v23, v103
	v_mul_f32_e32 v151, v7, v103
	ds_write2_b32 v125, v150, v151 offset0:192 offset1:224
.Lde_join:
	s_waitcnt lgkmcnt(0)
	s_barrier
	ds_read2_b32 v[64:65], v140 offset0:0 offset1:32
	ds_read2_b32 v[66:67], v140 offset0:64 offset1:96
	ds_read2_b32 v[68:69], v140 offset0:128 offset1:160
	ds_read2_b32 v[70:71], v140 offset0:192 offset1:224
	ds_read2_b32 v[72:73], v141 offset0:0 offset1:32
	ds_read2_b32 v[74:75], v141 offset0:64 offset1:96
	ds_read2_b32 v[76:77], v141 offset0:128 offset1:160
	ds_read2_b32 v[78:79], v141 offset0:192 offset1:224
	ds_read2_b32 v[80:81], v142 offset0:0 offset1:32
	ds_read2_b32 v[82:83], v142 offset0:64 offset1:96
	ds_read2_b32 v[84:85], v142 offset0:128 offset1:160
	ds_read2_b32 v[86:87], v142 offset0:192 offset1:224
	ds_read2_b32 v[88:89], v143 offset0:0 offset1:32
	ds_read2_b32 v[90:91], v143 offset0:64 offset1:96
	ds_read2_b32 v[92:93], v143 offset0:128 offset1:160
	ds_read2_b32 v[94:95], v143 offset0:192 offset1:224
	s_waitcnt lgkmcnt(14)
	v_sub_f32_e32 v194, v194, v64
	v_sub_f32_e32 v202, v202, v65
	v_sub_f32_e32 v210, v210, v66
	v_sub_f32_e32 v218, v218, v67
	v_mul_f32_e32 v152, v194, v194
	v_fmac_f32_e32 v152, v202, v202
	v_fmac_f32_e32 v152, v210, v210
	v_fmac_f32_e32 v152, v218, v218
	s_waitcnt lgkmcnt(12)
	v_sub_f32_e32 v195, v195, v68
	v_sub_f32_e32 v203, v203, v69
	v_sub_f32_e32 v211, v211, v70
	v_sub_f32_e32 v219, v219, v71
	v_mul_f32_e32 v153, v195, v195
	v_fmac_f32_e32 v153, v203, v203
	v_fmac_f32_e32 v153, v211, v211
	v_fmac_f32_e32 v153, v219, v219
	s_waitcnt lgkmcnt(10)
	v_sub_f32_e32 v196, v196, v72
	v_sub_f32_e32 v204, v204, v73
	v_sub_f32_e32 v212, v212, v74
	v_sub_f32_e32 v220, v220, v75
	v_mul_f32_e32 v154, v196, v196
	v_fmac_f32_e32 v154, v204, v204
	v_fmac_f32_e32 v154, v212, v212
	v_fmac_f32_e32 v154, v220, v220
	s_waitcnt lgkmcnt(8)
	v_sub_f32_e32 v197, v197, v76
	v_sub_f32_e32 v205, v205, v77
	v_sub_f32_e32 v213, v213, v78
	v_sub_f32_e32 v221, v221, v79
	v_mul_f32_e32 v155, v197, v197
	v_fmac_f32_e32 v155, v205, v205
	v_fmac_f32_e32 v155, v213, v213
	v_fmac_f32_e32 v155, v221, v221
	s_waitcnt lgkmcnt(6)
	v_sub_f32_e32 v198, v198, v80
	v_sub_f32_e32 v206, v206, v81
	v_sub_f32_e32 v214, v214, v82
	v_sub_f32_e32 v222, v222, v83
	v_mul_f32_e32 v126, v198, v198
	v_fmac_f32_e32 v126, v206, v206
	v_fmac_f32_e32 v126, v214, v214
	v_fmac_f32_e32 v126, v222, v222
	s_waitcnt lgkmcnt(4)
	v_sub_f32_e32 v199, v199, v84
	v_sub_f32_e32 v207, v207, v85
	v_sub_f32_e32 v215, v215, v86
	v_sub_f32_e32 v223, v223, v87
	v_mul_f32_e32 v127, v199, v199
	v_fmac_f32_e32 v127, v207, v207
	v_fmac_f32_e32 v127, v215, v215
	v_fmac_f32_e32 v127, v223, v223
	s_waitcnt lgkmcnt(2)
	v_sub_f32_e32 v200, v200, v88
	v_sub_f32_e32 v208, v208, v89
	v_sub_f32_e32 v216, v216, v90
	v_sub_f32_e32 v224, v224, v91
	v_mul_f32_e32 v128, v200, v200
	v_fmac_f32_e32 v128, v208, v208
	v_fmac_f32_e32 v128, v216, v216
	v_fmac_f32_e32 v128, v224, v224
	s_waitcnt lgkmcnt(0)
	v_sub_f32_e32 v201, v201, v92
	v_sub_f32_e32 v209, v209, v93
	v_sub_f32_e32 v217, v217, v94
	v_sub_f32_e32 v225, v225, v95
	v_mul_f32_e32 v161, v201, v201
	v_fmac_f32_e32 v161, v209, v209
	v_fmac_f32_e32 v161, v217, v217
	v_fmac_f32_e32 v161, v225, v225
	v_add_f32_dpp v152, v152, v152 quad_perm:[1,0,3,2] row_mask:0xf bank_mask:0xf
	v_add_f32_dpp v153, v153, v153 quad_perm:[1,0,3,2] row_mask:0xf bank_mask:0xf
	v_add_f32_dpp v154, v154, v154 quad_perm:[1,0,3,2] row_mask:0xf bank_mask:0xf
	v_add_f32_dpp v155, v155, v155 quad_perm:[1,0,3,2] row_mask:0xf bank_mask:0xf
	v_add_f32_dpp v126, v126, v126 quad_perm:[1,0,3,2] row_mask:0xf bank_mask:0xf
	v_add_f32_dpp v127, v127, v127 quad_perm:[1,0,3,2] row_mask:0xf bank_mask:0xf
	v_add_f32_dpp v128, v128, v128 quad_perm:[1,0,3,2] row_mask:0xf bank_mask:0xf
	v_add_f32_dpp v161, v161, v161 quad_perm:[1,0,3,2] row_mask:0xf bank_mask:0xf
	v_add_f32_dpp v152, v152, v152 quad_perm:[2,3,0,1] row_mask:0xf bank_mask:0xf
	v_add_f32_dpp v153, v153, v153 quad_perm:[2,3,0,1] row_mask:0xf bank_mask:0xf
	v_add_f32_dpp v154, v154, v154 quad_perm:[2,3,0,1] row_mask:0xf bank_mask:0xf
	v_add_f32_dpp v155, v155, v155 quad_perm:[2,3,0,1] row_mask:0xf bank_mask:0xf
	v_add_f32_dpp v126, v126, v126 quad_perm:[2,3,0,1] row_mask:0xf bank_mask:0xf
	v_add_f32_dpp v127, v127, v127 quad_perm:[2,3,0,1] row_mask:0xf bank_mask:0xf
	v_add_f32_dpp v128, v128, v128 quad_perm:[2,3,0,1] row_mask:0xf bank_mask:0xf
	v_add_f32_dpp v161, v161, v161 quad_perm:[2,3,0,1] row_mask:0xf bank_mask:0xf
	v_add_f32_dpp v152, v152, v152 row_half_mirror row_mask:0xf bank_mask:0xf
	v_add_f32_dpp v153, v153, v153 row_half_mirror row_mask:0xf bank_mask:0xf
	v_add_f32_dpp v154, v154, v154 row_half_mirror row_mask:0xf bank_mask:0xf
	v_add_f32_dpp v155, v155, v155 row_half_mirror row_mask:0xf bank_mask:0xf
	v_add_f32_dpp v126, v126, v126 row_half_mirror row_mask:0xf bank_mask:0xf
	v_add_f32_dpp v127, v127, v127 row_half_mirror row_mask:0xf bank_mask:0xf
	v_add_f32_dpp v128, v128, v128 row_half_mirror row_mask:0xf bank_mask:0xf
	v_add_f32_dpp v161, v161, v161 row_half_mirror row_mask:0xf bank_mask:0xf
	v_add_f32_dpp v152, v152, v152 row_mirror row_mask:0xf bank_mask:0xf
	v_add_f32_dpp v153, v153, v153 row_mirror row_mask:0xf bank_mask:0xf
	v_add_f32_dpp v154, v154, v154 row_mirror row_mask:0xf bank_mask:0xf
	v_add_f32_dpp v155, v155, v155 row_mirror row_mask:0xf bank_mask:0xf
	v_add_f32_dpp v126, v126, v126 row_mirror row_mask:0xf bank_mask:0xf
	v_add_f32_dpp v127, v127, v127 row_mirror row_mask:0xf bank_mask:0xf
	v_add_f32_dpp v128, v128, v128 row_mirror row_mask:0xf bank_mask:0xf
	v_add_f32_dpp v161, v161, v161 row_mirror row_mask:0xf bank_mask:0xf
	v_mov_b32_e32 v226, v152
	v_mov_b32_e32 v227, v153
	v_mov_b32_e32 v228, v154
	v_mov_b32_e32 v229, v155
	v_mov_b32_e32 v230, v126
	v_mov_b32_e32 v231, v127
	v_mov_b32_e32 v232, v128
	v_mov_b32_e32 v233, v161
	v_permlane16_swap_b32_e32 v152, v226
	v_permlane16_swap_b32_e32 v153, v227
	v_permlane16_swap_b32_e32 v154, v228
	v_permlane16_swap_b32_e32 v155, v229
	v_permlane16_swap_b32_e32 v126, v230
	v_permlane16_swap_b32_e32 v127, v231
	v_permlane16_swap_b32_e32 v128, v232
	v_permlane16_swap_b32_e32 v161, v233
	v_add_f32_e32 v152, v152, v226
	v_add_f32_e32 v153, v153, v227
	v_add_f32_e32 v154, v154, v228
	v_add_f32_e32 v155, v155, v229
	v_add_f32_e32 v126, v126, v230
	v_add_f32_e32 v127, v127, v231
	v_add_f32_e32 v128, v128, v232
	v_add_f32_e32 v161, v161, v233
	v_fmamk_f32 v152, v152, 0x3c000000, v138
	v_fmamk_f32 v153, v153, 0x3c000000, v138
	v_fmamk_f32 v154, v154, 0x3c000000, v138
	v_fmamk_f32 v155, v155, 0x3c000000, v138
	v_fmamk_f32 v126, v126, 0x3c000000, v138
	v_fmamk_f32 v127, v127, 0x3c000000, v138
	v_fmamk_f32 v128, v128, 0x3c000000, v138
	v_fmamk_f32 v161, v161, 0x3c000000, v138
	v_rsq_f32_e32 v152, v152
	v_rsq_f32_e32 v153, v153
	v_rsq_f32_e32 v154, v154
	v_rsq_f32_e32 v155, v155
	v_rsq_f32_e32 v126, v126
	v_rsq_f32_e32 v127, v127
	v_rsq_f32_e32 v128, v128
	v_rsq_f32_e32 v161, v161
	s_waitcnt vmcnt(0)
	v_mul_f32_e32 v194, v194, v152
	v_lshlrev_b32_e32 v162, 16, v162
	v_mul_f32_e32 v194, v112, v194
	v_mul_f32_e32 v194, v194, v162
	v_cvt_pk_bf16_f32 v194, v194, v194
	v_mul_f32_e32 v202, v202, v152
	v_lshlrev_b32_e32 v163, 16, v163
	v_mul_f32_e32 v202, v113, v202
	v_mul_f32_e32 v202, v202, v163
	v_cvt_pk_bf16_f32 v202, v202, v202
	v_mul_f32_e32 v210, v210, v152
	v_lshlrev_b32_e32 v164, 16, v164
	v_mul_f32_e32 v210, v114, v210
	v_mul_f32_e32 v210, v210, v164
	v_cvt_pk_bf16_f32 v210, v210, v210
	v_mul_f32_e32 v218, v218, v152
	v_lshlrev_b32_e32 v165, 16, v165
	v_mul_f32_e32 v218, v115, v218
	v_mul_f32_e32 v218, v218, v165
	v_cvt_pk_bf16_f32 v218, v218, v218
	global_store_short v119, v194, s[46:47] offset:0
	global_store_short v119, v202, s[46:47] offset:64
	global_store_short v119, v210, s[46:47] offset:128
	global_store_short v119, v218, s[46:47] offset:192
	s_add_u32 s46, s46, 0x800
	s_addc_u32 s47, s47, 0
	v_mul_f32_e32 v195, v195, v153
	v_lshlrev_b32_e32 v166, 16, v166
	v_mul_f32_e32 v195, v112, v195
	v_mul_f32_e32 v195, v195, v166
	v_cvt_pk_bf16_f32 v195, v195, v195
	v_mul_f32_e32 v203, v203, v153
	v_lshlrev_b32_e32 v167, 16, v167
	v_mul_f32_e32 v203, v113, v203
	v_mul_f32_e32 v203, v203, v167
	v_cvt_pk_bf16_f32 v203, v203, v203
	v_mul_f32_e32 v211, v211, v153
	v_lshlrev_b32_e32 v168, 16, v168
	v_mul_f32_e32 v211, v114, v211
	v_mul_f32_e32 v211, v211, v168
	v_cvt_pk_bf16_f32 v211, v211, v211
	v_mul_f32_e32 v219, v219, v153
	v_lshlrev_b32_e32 v169, 16, v169
	v_mul_f32_e32 v219, v115, v219
	v_mul_f32_e32 v219, v219, v169
	v_cvt_pk_bf16_f32 v219, v219, v219
	global_store_short v119, v195, s[46:47] offset:0
	global_store_short v119, v203, s[46:47] offset:64
	global_store_short v119, v211, s[46:47] offset:128
	global_store_short v119, v219, s[46:47] offset:192
	s_add_u32 s46, s46, 0x800
	s_addc_u32 s47, s47, 0
	v_mul_f32_e32 v196, v196, v154
	v_lshlrev_b32_e32 v170, 16, v170
	v_mul_f32_e32 v196, v112, v196
	v_mul_f32_e32 v196, v196, v170
	v_cvt_pk_bf16_f32 v196, v196, v196
	v_mul_f32_e32 v204, v204, v154
	v_lshlrev_b32_e32 v171, 16, v171
	v_mul_f32_e32 v204, v113, v204
	v_mul_f32_e32 v204, v204, v171
	v_cvt_pk_bf16_f32 v204, v204, v204
	v_mul_f32_e32 v212, v212, v154
	v_lshlrev_b32_e32 v172, 16, v172
	v_mul_f32_e32 v212, v114, v212
	v_mul_f32_e32 v212, v212, v172
	v_cvt_pk_bf16_f32 v212, v212, v212
	v_mul_f32_e32 v220, v220, v154
	v_lshlrev_b32_e32 v173, 16, v173
	v_mul_f32_e32 v220, v115, v220
	v_mul_f32_e32 v220, v220, v173
	v_cvt_pk_bf16_f32 v220, v220, v220
	global_store_short v119, v196, s[46:47] offset:0
	global_store_short v119, v204, s[46:47] offset:64
	global_store_short v119, v212, s[46:47] offset:128
	global_store_short v119, v220, s[46:47] offset:192
	s_add_u32 s46, s46, 0x800
	s_addc_u32 s47, s47, 0
	v_mul_f32_e32 v197, v197, v155
	v_lshlrev_b32_e32 v174, 16, v174
	v_mul_f32_e32 v197, v112, v197
	v_mul_f32_e32 v197, v197, v174
	v_cvt_pk_bf16_f32 v197, v197, v197
	v_mul_f32_e32 v205, v205, v155
	v_lshlrev_b32_e32 v175, 16, v175
	v_mul_f32_e32 v205, v113, v205
	v_mul_f32_e32 v205, v205, v175
	v_cvt_pk_bf16_f32 v205, v205, v205
	v_mul_f32_e32 v213, v213, v155
	v_lshlrev_b32_e32 v176, 16, v176
	v_mul_f32_e32 v213, v114, v213
	v_mul_f32_e32 v213, v213, v176
	v_cvt_pk_bf16_f32 v213, v213, v213
	v_mul_f32_e32 v221, v221, v155
	v_lshlrev_b32_e32 v177, 16, v177
	v_mul_f32_e32 v221, v115, v221
	v_mul_f32_e32 v221, v221, v177
	v_cvt_pk_bf16_f32 v221, v221, v221
	global_store_short v119, v197, s[46:47] offset:0
	global_store_short v119, v205, s[46:47] offset:64
	global_store_short v119, v213, s[46:47] offset:128
	global_store_short v119, v221, s[46:47] offset:192
	s_add_u32 s46, s46, 0x2800
	s_addc_u32 s47, s47, 0
	v_mul_f32_e32 v198, v198, v126
	v_lshlrev_b32_e32 v178, 16, v178
	v_mul_f32_e32 v198, v112, v198
	v_mul_f32_e32 v198, v198, v178
	v_cvt_pk_bf16_f32 v198, v198, v198
	v_mul_f32_e32 v206, v206, v126
	v_lshlrev_b32_e32 v179, 16, v179
	v_mul_f32_e32 v206, v113, v206
	v_mul_f32_e32 v206, v206, v179
	v_cvt_pk_bf16_f32 v206, v206, v206
	v_mul_f32_e32 v214, v214, v126
	v_lshlrev_b32_e32 v180, 16, v180
	v_mul_f32_e32 v214, v114, v214
	v_mul_f32_e32 v214, v214, v180
	v_cvt_pk_bf16_f32 v214, v214, v214
	v_mul_f32_e32 v222, v222, v126
	v_lshlrev_b32_e32 v181, 16, v181
	v_mul_f32_e32 v222, v115, v222
	v_mul_f32_e32 v222, v222, v181
	v_cvt_pk_bf16_f32 v222, v222, v222
	global_store_short v119, v198, s[46:47] offset:0
	global_store_short v119, v206, s[46:47] offset:64
	global_store_short v119, v214, s[46:47] offset:128
	global_store_short v119, v222, s[46:47] offset:192
	s_add_u32 s46, s46, 0x800
	s_addc_u32 s47, s47, 0
	v_mul_f32_e32 v199, v199, v127
	v_lshlrev_b32_e32 v182, 16, v182
	v_mul_f32_e32 v199, v112, v199
	v_mul_f32_e32 v199, v199, v182
	v_cvt_pk_bf16_f32 v199, v199, v199
	v_mul_f32_e32 v207, v207, v127
	v_lshlrev_b32_e32 v183, 16, v183
	v_mul_f32_e32 v207, v113, v207
	v_mul_f32_e32 v207, v207, v183
	v_cvt_pk_bf16_f32 v207, v207, v207
	v_mul_f32_e32 v215, v215, v127
	v_lshlrev_b32_e32 v184, 16, v184
	v_mul_f32_e32 v215, v114, v215
	v_mul_f32_e32 v215, v215, v184
	v_cvt_pk_bf16_f32 v215, v215, v215
	v_mul_f32_e32 v223, v223, v127
	v_lshlrev_b32_e32 v185, 16, v185
	v_mul_f32_e32 v223, v115, v223
	v_mul_f32_e32 v223, v223, v185
	v_cvt_pk_bf16_f32 v223, v223, v223
	global_store_short v119, v199, s[46:47] offset:0
	global_store_short v119, v207, s[46:47] offset:64
	global_store_short v119, v215, s[46:47] offset:128
	global_store_short v119, v223, s[46:47] offset:192
	s_add_u32 s46, s46, 0x800
	s_addc_u32 s47, s47, 0
	v_mul_f32_e32 v200, v200, v128
	v_lshlrev_b32_e32 v186, 16, v186
	v_mul_f32_e32 v200, v112, v200
	v_mul_f32_e32 v200, v200, v186
	v_cvt_pk_bf16_f32 v200, v200, v200
	v_mul_f32_e32 v208, v208, v128
	v_lshlrev_b32_e32 v187, 16, v187
	v_mul_f32_e32 v208, v113, v208
	v_mul_f32_e32 v208, v208, v187
	v_cvt_pk_bf16_f32 v208, v208, v208
	v_mul_f32_e32 v216, v216, v128
	v_lshlrev_b32_e32 v188, 16, v188
	v_mul_f32_e32 v216, v114, v216
	v_mul_f32_e32 v216, v216, v188
	v_cvt_pk_bf16_f32 v216, v216, v216
	v_mul_f32_e32 v224, v224, v128
	v_lshlrev_b32_e32 v189, 16, v189
	v_mul_f32_e32 v224, v115, v224
	v_mul_f32_e32 v224, v224, v189
	v_cvt_pk_bf16_f32 v224, v224, v224
	global_store_short v119, v200, s[46:47] offset:0
	global_store_short v119, v208, s[46:47] offset:64
	global_store_short v119, v216, s[46:47] offset:128
	global_store_short v119, v224, s[46:47] offset:192
	s_add_u32 s46, s46, 0x800
	s_addc_u32 s47, s47, 0
	v_mul_f32_e32 v201, v201, v161
	v_lshlrev_b32_e32 v190, 16, v190
	v_mul_f32_e32 v201, v112, v201
	v_mul_f32_e32 v201, v201, v190
	v_cvt_pk_bf16_f32 v201, v201, v201
	v_mul_f32_e32 v209, v209, v161
	v_lshlrev_b32_e32 v191, 16, v191
	v_mul_f32_e32 v209, v113, v209
	v_mul_f32_e32 v209, v209, v191
	v_cvt_pk_bf16_f32 v209, v209, v209
	v_mul_f32_e32 v217, v217, v161
	v_lshlrev_b32_e32 v192, 16, v192
	v_mul_f32_e32 v217, v114, v217
	v_mul_f32_e32 v217, v217, v192
	v_cvt_pk_bf16_f32 v217, v217, v217
	v_mul_f32_e32 v225, v225, v161
	v_lshlrev_b32_e32 v193, 16, v193
	v_mul_f32_e32 v225, v115, v225
	v_mul_f32_e32 v225, v225, v193
	v_cvt_pk_bf16_f32 v225, v225, v225
	global_store_short v119, v201, s[46:47] offset:0
	global_store_short v119, v209, s[46:47] offset:64
	global_store_short v119, v217, s[46:47] offset:128
	global_store_short v119, v225, s[46:47] offset:192
	s_branch .LBB0_286
